# plus: LN1 router set-up loads issued eight steps ahead; GQA next-unit Q fragments prefetched during the last key tile
# speedup vs baseline: 1.0203x; 1.0080x over previous
.LBB0_287:
	s_andn2_b64 vcc, exec, s[16:17]
	s_mov_b64 s[66:67], 0xf80000
	s_cbranch_vccnz .LBB0_296
	s_and_b64 vcc, exec, s[38:39]
	s_cbranch_vccnz .LBB0_296
	s_add_u32 s38, s36, 0x18040b00
	s_addc_u32 s39, s37, 0
	s_add_u32 s44, s36, 0x18040a00
	s_addc_u32 s45, s37, 0
	s_mov_b32 s78, 0
	s_branch .LBB0_291

.LBB0_291:
	s_ashr_i32 s16, s19, 7
	s_ashr_i32 s17, s16, 31
	s_lshl_b32 s24, s19, 8
	s_lshl_b64 s[40:41], s[16:17], 12
	s_and_b32 s24, s24, 0xf00
	s_bfe_u32 s36, s19, 0x10006
	s_or_b32 s40, s40, s24
	s_lshl_b32 s60, s36, 7
	s_lshl_b64 s[24:25], s[40:41], 12
	s_add_u32 s24, s50, s24
	s_addc_u32 s25, s51, s25
	s_lshl_b32 s37, s19, 2
	s_lshl_b32 s36, s36, 8
	s_and_b32 s37, s37, 0xc0
	s_or_b32 s47, s36, s37
	s_lshl_b32 s36, s47, 1
	s_add_u32 s48, s24, s36
	s_addc_u32 s49, s25, 0
	s_lshl_b64 s[16:17], s[16:17], 24
	s_add_u32 s24, s50, s16
	s_addc_u32 s25, s51, s17
	v_mov_b32_e32 v72, v192
	s_add_u32 s42, s24, s60
	s_addc_u32 s43, s25, 0
	v_readfirstlane_b32 s55, v72
	s_ashr_i32 s46, s55, 6
	s_lshl_b32 s36, s46, 5
	s_ashr_i32 s37, s36, 31
	s_lshl_b64 s[24:25], s[36:37], 12
	s_add_u32 s56, s48, s24
	v_and_b32_e32 v160, 63, v72
	s_addc_u32 s57, s49, s25
	s_mov_b64 s[76:77], s[56:57]
	s_lshl_b32 s24, s46, 3
	v_lshlrev_b32_e32 v188, 12, v160
	s_ashr_i32 s25, s24, 31
	v_lshl_add_u64 v[0:1], s[42:43], 0, v[188:189]
	s_lshl_b64 s[24:25], s[24:25], 1
	v_lshl_add_u64 v[40:41], v[0:1], 0, s[24:25]
	s_mov_b64 s[48:49], 0xa00
	v_lshl_add_u64 v[154:155], v[40:41], 0, s[48:49]
	s_lshl_b32 s48, s46, 4
	v_bfe_u32 v73, v72, 2, 4
	v_and_or_b32 v0, s48, 48, v73
	v_lshlrev_b32_e32 v0, 12, v0
	v_mov_b32_e32 v1, v189
	v_lshl_add_u64 v[0:1], s[42:43], 0, v[0:1]
	s_ashr_i32 s42, s55, 3
	s_andn2_b32 s42, s42, 31
	s_ashr_i32 s43, s42, 31
	v_lshlrev_b32_e32 v161, 3, v72
	s_lshl_b64 s[42:43], s[42:43], 1
	v_and_b32_e32 v166, 24, v161
	v_lshl_add_u64 v[0:1], v[0:1], 0, s[42:43]
	v_lshlrev_b32_e32 v2, 1, v166
	v_mov_b32_e32 v3, v189
	s_lshl_b32 s54, s46, 10
	v_lshl_add_u64 v[64:65], v[0:1], 0, v[2:3]
	s_mov_b64 s[48:49], 0xb00
	s_cmp_lg_u32 0, -1
	v_lshl_add_u64 v[152:153], v[64:65], 0, s[48:49]
	s_cselect_b32 s48, 0, 0
	s_add_i32 s49, s54, s48
	s_mov_b32 s58, m0
	s_mov_b32 m0, s49
	s_nop 0
	global_load_lds_dwordx4 v[154:155], off
	s_mov_b32 m0, s58
	s_add_i32 s48, s49, 0x6000
	s_mov_b32 s58, m0
	s_mov_b32 m0, s48
	s_nop 0
	global_load_lds_dwordx4 v[152:153], off
	s_mov_b32 m0, s58
	s_mov_b64 s[58:59], 0x40a00
	v_and_b32_e32 v162, 31, v72
	v_lshl_add_u64 v[0:1], v[40:41], 0, s[58:59]
	v_bfe_u32 v163, v72, 5, 1
	s_add_i32 s58, s49, 0x2000
	s_mov_b32 s59, m0
	s_mov_b32 m0, s58
	s_nop 0
	global_load_lds_dwordx4 v[0:1], off
	s_mov_b32 m0, s59
	v_lshlrev_b32_e32 v0, 12, v162
	v_lshl_or_b32 v0, v163, 4, v0
	s_cmp_lg_u32 s78, 0
	s_cbranch_scc1 .Lgqa_q_have
	global_load_dwordx4 v[140:143], v0, s[56:57] offset:1536
	global_load_dwordx4 v[132:135], v0, s[56:57] offset:1568
	global_load_dwordx4 v[124:127], v0, s[56:57] offset:1600
	global_load_dwordx4 v[116:119], v0, s[56:57] offset:1632
.Lgqa_q_have:
	v_lshlrev_b32_e32 v0, 10, v163
	v_lshlrev_b32_e32 v1, 4, v162
	s_mov_b64 s[56:57], 0x80a00
	v_add3_u32 v165, 0, v0, v1
	v_lshl_add_u64 v[0:1], v[40:41], 0, s[56:57]
	s_add_i32 s56, s49, 0x4000
	s_mov_b32 s57, m0
	s_mov_b32 m0, s56
	s_nop 0
	global_load_lds_dwordx4 v[0:1], off
	s_mov_b32 m0, s57
	s_waitcnt vmcnt(3) lgkmcnt(0)
	s_barrier
	s_cmp_eq_u32 s78, 0
	s_cbranch_scc1 .Lgqa_nomov
	v_mov_b32_e32 v140, v196
	v_mov_b32_e32 v141, v197
	v_mov_b32_e32 v142, v198
	v_mov_b32_e32 v143, v199
	v_mov_b32_e32 v132, v200
	v_mov_b32_e32 v133, v201
	v_mov_b32_e32 v134, v202
	v_mov_b32_e32 v135, v203
	v_mov_b32_e32 v124, v204
	v_mov_b32_e32 v125, v205
	v_mov_b32_e32 v126, v206
	v_mov_b32_e32 v127, v207
	v_mov_b32_e32 v116, v208
	v_mov_b32_e32 v117, v209
	v_mov_b32_e32 v118, v210
	v_mov_b32_e32 v119, v211
.Lgqa_nomov:
	ds_read_b128 v[0:3], v165
	ds_read_b128 v[4:7], v165 offset:512
	ds_read_b128 v[32:35], v165 offset:2048
	ds_read_b128 v[36:39], v165 offset:2560
	v_lshlrev_b32_e32 v42, 1, v72
	v_and_b32_e32 v168, 32, v42
	s_mov_b64 s[62:63], 0xc0a00
	v_lshl_add_u64 v[66:67], v[40:41], 0, s[62:63]
	s_mov_b64 s[62:63], 0x40b00
	v_mov_b32_e32 v167, 0
	s_mov_b32 s56, -1
	s_mov_b32 s59, 0
	s_movk_i32 s58, 0x2000
	s_movk_i32 s57, 0x4000
	s_waitcnt vmcnt(3) lgkmcnt(3)
	v_mfma_f32_32x32x16_bf16 v[16:31], v[0:3], v[140:143], 0
	s_waitcnt lgkmcnt(2)
	v_mfma_f32_32x32x16_bf16 v[0:15], v[4:7], v[140:143], 0
	s_waitcnt vmcnt(2) lgkmcnt(1)
	v_mfma_f32_32x32x16_bf16 v[16:31], v[32:35], v[132:135], v[16:31]
	s_waitcnt lgkmcnt(0)
	v_mfma_f32_32x32x16_bf16 v[0:15], v[36:39], v[132:135], v[0:15]
	ds_read_b128 v[32:35], v165 offset:4096
	ds_read_b128 v[36:39], v165 offset:4608
	s_waitcnt vmcnt(1) lgkmcnt(1)
	v_mfma_f32_32x32x16_bf16 v[16:31], v[32:35], v[124:127], v[16:31]
	ds_read_b128 v[32:35], v165 offset:6144
	s_waitcnt lgkmcnt(1)
	v_mfma_f32_32x32x16_bf16 v[0:15], v[36:39], v[124:127], v[0:15]
	ds_read_b128 v[36:39], v165 offset:6656
	s_waitcnt vmcnt(0) lgkmcnt(1)
	v_mfma_f32_32x32x16_bf16 v[16:31], v[32:35], v[116:119], v[16:31]
	v_lshlrev_b32_e32 v32, 4, v72
	v_and_b32_e32 v32, 0xc0, v32
	v_lshl_or_b32 v169, v163, 8, v32
	v_add_u32_e32 v32, 0, v168
	v_add3_u32 v164, v32, v166, v169
	s_waitcnt lgkmcnt(0)
	v_mfma_f32_32x32x16_bf16 v[0:15], v[36:39], v[116:119], v[0:15]
	s_nop 15
	s_nop 7
	s_waitcnt vmcnt(0) lgkmcnt(0)
	s_barrier
	s_mov_b32 s61, m0
	s_mov_b32 m0, s49
	s_nop 0
	global_load_lds_dwordx4 v[66:67], off
	s_mov_b32 m0, s61
	s_add_i32 s61, s49, 0x8000
	s_nop 3
	v_exp_f32_e32 v48, v16
	s_nop 5
	v_exp_f32_e32 v32, v0
	v_exp_f32_e32 v33, v1
	v_lshl_add_u64 v[0:1], v[64:65], 0, s[62:63]
	s_mov_b32 s62, m0
	s_mov_b32 m0, s61
	s_nop 0
	global_load_lds_dwordx4 v[0:1], off
	s_mov_b32 m0, s62
	ds_read_b128 v[68:71], v165 offset:8192
	ds_read_b128 v[64:67], v165 offset:8704
	ds_read_b128 v[148:151], v165 offset:10240
	ds_read_b128 v[144:147], v165 offset:10752
	ds_read_b128 v[108:111], v165 offset:12288
	ds_read_b128 v[104:107], v165 offset:12800
	ds_read_b128 v[100:103], v165 offset:14336
	ds_read_b128 v[96:99], v165 offset:14848
	s_or_b32 s61, s16, s60
	v_and_b32_e32 v0, 3, v72
	s_add_u32 s42, s42, s61
	s_addc_u32 s43, s43, s17
	v_lshl_or_b32 v0, v0, 4, s42
	s_lshl_b32 s42, s46, 16
	s_and_b32 s42, s42, 0x30000
	s_add_u32 s24, s44, s24
	s_addc_u32 s25, s45, s25
	s_add_u32 s24, s24, s60
	v_exp_f32_e32 v49, v17
	v_exp_f32_e32 v50, v18
	v_exp_f32_e32 v51, v19
	v_exp_f32_e32 v52, v20
	v_exp_f32_e32 v53, v21
	v_exp_f32_e32 v54, v22
	v_exp_f32_e32 v55, v23
	v_exp_f32_e32 v56, v24
	v_exp_f32_e32 v57, v25
	v_exp_f32_e32 v58, v26
	v_exp_f32_e32 v59, v27
	v_exp_f32_e32 v60, v28
	v_exp_f32_e32 v61, v29
	v_exp_f32_e32 v62, v30
	v_exp_f32_e32 v63, v31
	v_exp_f32_e32 v34, v2
	v_exp_f32_e32 v35, v3
	v_exp_f32_e32 v36, v4
	v_exp_f32_e32 v37, v5
	v_exp_f32_e32 v38, v6
	v_exp_f32_e32 v39, v7
	v_exp_f32_e32 v40, v8
	v_exp_f32_e32 v41, v9
	v_exp_f32_e32 v42, v10
	v_exp_f32_e32 v43, v11
	v_exp_f32_e32 v44, v12
	v_exp_f32_e32 v45, v13
	v_exp_f32_e32 v46, v14
	v_exp_f32_e32 v47, v15
	s_addc_u32 s25, s25, 0
	s_waitcnt vmcnt(2) lgkmcnt(0)
	s_barrier
	v_mov_b32_e32 v1, s43
	v_lshl_or_b32 v2, v73, 12, s42
	v_mov_b32_e32 v3, v189
	s_add_u32 s16, s24, s16
	v_lshl_add_u64 v[0:1], v[0:1], 0, v[2:3]
	s_addc_u32 s17, s25, s17
	v_lshl_add_u64 v[156:157], s[38:39], 0, v[0:1]
	v_lshl_add_u64 v[158:159], s[16:17], 0, v[188:189]
	v_mov_b32_e32 v0, 0
	v_mov_b32_e32 v1, v167
	v_mov_b32_e32 v2, v167
	v_mov_b32_e32 v3, v167
	v_mov_b32_e32 v4, v167
	v_mov_b32_e32 v5, v167
	v_mov_b32_e32 v6, v167
	v_mov_b32_e32 v7, v167
	v_mov_b32_e32 v8, v167
	v_mov_b32_e32 v9, v167
	v_mov_b32_e32 v10, v167
	v_mov_b32_e32 v11, v167
	v_mov_b32_e32 v12, v167
	v_mov_b32_e32 v13, v167
	v_mov_b32_e32 v14, v167
	v_mov_b32_e32 v15, v167
	v_mov_b32_e32 v16, 0
	v_mov_b32_e32 v17, v167
	v_mov_b32_e32 v18, v167
	v_mov_b32_e32 v19, v167
	v_mov_b32_e32 v20, v167
	v_mov_b32_e32 v21, v167
	v_mov_b32_e32 v22, v167
	v_mov_b32_e32 v23, v167
	v_mov_b32_e32 v24, v167
	v_mov_b32_e32 v25, v167
	v_mov_b32_e32 v26, v167
	v_mov_b32_e32 v27, v167
	v_mov_b32_e32 v28, v167
	v_mov_b32_e32 v29, v167
	v_mov_b32_e32 v30, v167
	v_mov_b32_e32 v31, v167
.LBB0_292:
	v_add_u32_e32 v170, s59, v164
	ds_read_b64_tr_b16 v[172:173], v170 offset:24576
	ds_read_b64_tr_b16 v[174:175], v170 offset:25088
	v_add_f32_e32 v72, v48, v49
	v_add_f32_e32 v72, v50, v72
	v_add_f32_e32 v72, v51, v72
	v_add_f32_e32 v72, v52, v72
	v_add_f32_e32 v72, v53, v72
	v_cvt_pk_bf16_f32 v136, v48, v49
	v_cvt_pk_bf16_f32 v137, v50, v51
	s_waitcnt lgkmcnt(9)
	v_mfma_f32_32x32x16_bf16 v[80:95], v[68:71], v[140:143], 0
	ds_read_b64_tr_b16 v[48:49], v170 offset:28672
	ds_read_b64_tr_b16 v[50:51], v170 offset:29184
	v_add_f32_e32 v68, v54, v72
	v_add_f32_e32 v68, v55, v68
	v_add_f32_e32 v68, v56, v68
	v_add_f32_e32 v112, v57, v68
	s_waitcnt lgkmcnt(10)
	v_mfma_f32_32x32x16_bf16 v[64:79], v[64:67], v[140:143], 0
	v_cvt_pk_bf16_f32 v138, v52, v53
	v_cvt_pk_bf16_f32 v139, v54, v55
	ds_read_b64_tr_b16 v[52:53], v170 offset:25600
	ds_read_b64_tr_b16 v[54:55], v170 offset:26112
	v_add_f32_e32 v112, v58, v112
	v_add_f32_e32 v112, v59, v112
	v_add_f32_e32 v112, v60, v112
	v_add_f32_e32 v112, v61, v112
	v_cvt_pk_bf16_f32 v128, v56, v57
	v_cvt_pk_bf16_f32 v129, v58, v59
	s_waitcnt lgkmcnt(11)
	v_mfma_f32_32x32x16_bf16 v[80:95], v[148:151], v[132:135], v[80:95]
	ds_read_b64_tr_b16 v[56:57], v170 offset:29696
	ds_read_b64_tr_b16 v[58:59], v170 offset:30208
	s_waitcnt lgkmcnt(12)
	v_mfma_f32_32x32x16_bf16 v[64:79], v[144:147], v[132:135], v[64:79]
	v_add_f32_e32 v112, v62, v112
	v_add_f32_e32 v112, v63, v112
	v_add_f32_e32 v112, v32, v112
	v_add_f32_e32 v112, v33, v112
	v_cvt_pk_bf16_f32 v130, v60, v61
	v_cvt_pk_bf16_f32 v131, v62, v63
	ds_read_b64_tr_b16 v[60:61], v170 offset:26624
	ds_read_b64_tr_b16 v[62:63], v170 offset:27136
	s_waitcnt lgkmcnt(13)
	v_mfma_f32_32x32x16_bf16 v[80:95], v[108:111], v[124:127], v[80:95]
	v_add_f32_e32 v108, v34, v112
	v_add_f32_e32 v108, v35, v108
	v_add_f32_e32 v108, v36, v108
	v_add_f32_e32 v108, v37, v108
	v_cvt_pk_bf16_f32 v120, v32, v33
	v_cvt_pk_bf16_f32 v121, v34, v35
	ds_read_b64_tr_b16 v[32:33], v170 offset:30720
	ds_read_b64_tr_b16 v[34:35], v170 offset:31232
	s_waitcnt lgkmcnt(14)
	v_mfma_f32_32x32x16_bf16 v[64:79], v[104:107], v[124:127], v[64:79]
	v_add_f32_e32 v104, v38, v108
	v_add_f32_e32 v104, v39, v104
	v_add_f32_e32 v104, v40, v104
	v_add_f32_e32 v104, v41, v104
	v_cvt_pk_bf16_f32 v122, v36, v37
	v_cvt_pk_bf16_f32 v123, v38, v39
	ds_read_b64_tr_b16 v[36:37], v170 offset:27648
	ds_read_b64_tr_b16 v[38:39], v170 offset:28160
	s_waitcnt lgkmcnt(14)
	v_mfma_f32_32x32x16_bf16 v[80:95], v[100:103], v[116:119], v[80:95]
	v_add_f32_e32 v100, v42, v104
	v_add_f32_e32 v100, v43, v100
	v_add_f32_e32 v100, v44, v100
	v_add_f32_e32 v100, v45, v100
	v_cvt_pk_bf16_f32 v112, v40, v41
	v_cvt_pk_bf16_f32 v113, v42, v43
	ds_read_b64_tr_b16 v[40:41], v170 offset:31744
	ds_read_b64_tr_b16 v[42:43], v170 offset:32256
	v_mfma_f32_32x32x16_bf16 v[64:79], v[96:99], v[116:119], v[64:79]
	v_add_f32_e32 v96, v46, v100
	v_add_f32_e32 v96, v47, v96
	v_add_f32_e32 v170, 0, v96
	v_cvt_pk_bf16_f32 v114, v44, v45
	v_cvt_pk_bf16_f32 v115, v46, v47
	v_lshl_add_u64 v[44:45], v[158:159], 0, s[20:21]
	s_add_i32 s16, s58, s49
	s_mov_b32 s17, m0
	s_mov_b32 m0, s16
	s_nop 0
	global_load_lds_dwordx4 v[44:45], off
	s_mov_b32 m0, s17
	v_lshl_add_u64 v[44:45], v[156:157], 0, s[26:27]
	s_add_i32 s16, s57, s48
	s_mov_b32 s17, m0
	s_mov_b32 m0, s16
	s_nop 0
	global_load_lds_dwordx4 v[44:45], off
	s_mov_b32 m0, s17
	s_waitcnt lgkmcnt(14)
	v_mfma_f32_32x32x16_bf16 v[0:15], v[136:139], v[172:175], v[0:15]
	v_exp_f32_e32 v80, v80
	v_exp_f32_e32 v81, v81
	v_exp_f32_e32 v82, v82
	v_exp_f32_e32 v83, v83
	s_waitcnt lgkmcnt(12)
	v_mfma_f32_32x32x16_bf16 v[16:31], v[136:139], v[48:51], v[16:31]
	v_exp_f32_e32 v84, v84
	v_exp_f32_e32 v85, v85
	v_exp_f32_e32 v86, v86
	v_exp_f32_e32 v87, v87
	v_add_u32_e32 v48, s57, v165
	ds_read_b128 v[44:47], v48
	ds_read_b128 v[100:103], v48 offset:512
	s_waitcnt lgkmcnt(12)
	v_mfma_f32_32x32x16_bf16 v[0:15], v[128:131], v[52:55], v[0:15]
	v_exp_f32_e32 v88, v88
	v_exp_f32_e32 v89, v89
	v_exp_f32_e32 v90, v90
	v_exp_f32_e32 v91, v91
	ds_read_b128 v[104:107], v48 offset:2048
	ds_read_b128 v[108:111], v48 offset:2560
	s_waitcnt lgkmcnt(12)
	v_mfma_f32_32x32x16_bf16 v[16:31], v[128:131], v[56:59], v[16:31]
	v_exp_f32_e32 v92, v92
	v_exp_f32_e32 v93, v93
	v_exp_f32_e32 v94, v94
	v_exp_f32_e32 v95, v95
	ds_read_b128 v[144:147], v48 offset:4096
	ds_read_b128 v[148:151], v48 offset:4608
	s_waitcnt lgkmcnt(12)
	v_mfma_f32_32x32x16_bf16 v[0:15], v[120:123], v[60:63], v[0:15]
	v_exp_f32_e32 v64, v64
	v_exp_f32_e32 v65, v65
	v_exp_f32_e32 v66, v66
	v_exp_f32_e32 v67, v67
	ds_read_b128 v[172:175], v48 offset:6144
	ds_read_b128 v[96:99], v48 offset:6656
	s_waitcnt lgkmcnt(12)
	v_mfma_f32_32x32x16_bf16 v[16:31], v[120:123], v[32:35], v[16:31]
	v_exp_f32_e32 v68, v68
	v_exp_f32_e32 v69, v69
	v_exp_f32_e32 v70, v70
	v_exp_f32_e32 v71, v71
	s_waitcnt lgkmcnt(10)
	v_mfma_f32_32x32x16_bf16 v[0:15], v[112:115], v[36:39], v[0:15]
	v_exp_f32_e32 v72, v72
	v_exp_f32_e32 v73, v73
	v_exp_f32_e32 v74, v74
	v_exp_f32_e32 v75, v75
	s_waitcnt lgkmcnt(8)
	v_mfma_f32_32x32x16_bf16 v[16:31], v[112:115], v[40:43], v[16:31]
	v_exp_f32_e32 v76, v76
	v_exp_f32_e32 v77, v77
	v_exp_f32_e32 v78, v78
	v_exp_f32_e32 v79, v79
	s_waitcnt vmcnt(2) lgkmcnt(0)
	s_barrier
	s_add_i32 s16, s57, 0x2000
	s_cmpk_lg_i32 s57, 0x4000
	s_cselect_b32 s16, s16, 0
	v_add_u32_e32 v171, s58, v164
	ds_read_b64_tr_b16 v[176:177], v171 offset:24576
	ds_read_b64_tr_b16 v[178:179], v171 offset:25088
	s_waitcnt lgkmcnt(9)
	v_mfma_f32_32x32x16_bf16 v[48:63], v[44:47], v[140:143], 0
	v_add_f32_e32 v32, v80, v81
	v_add_f32_e32 v32, v82, v32
	v_add_f32_e32 v32, v83, v32
	v_add_f32_e32 v32, v84, v32
	v_add_f32_e32 v32, v85, v32
	v_cvt_pk_bf16_f32 v136, v80, v81
	v_cvt_pk_bf16_f32 v137, v82, v83
	ds_read_b64_tr_b16 v[80:81], v171 offset:28672
	ds_read_b64_tr_b16 v[82:83], v171 offset:29184
	v_add_f32_e32 v32, v86, v32
	v_add_f32_e32 v32, v87, v32
	v_add_f32_e32 v32, v88, v32
	v_add_f32_e32 v112, v89, v32
	s_waitcnt lgkmcnt(10)
	v_mfma_f32_32x32x16_bf16 v[32:47], v[100:103], v[140:143], 0
	v_cvt_pk_bf16_f32 v138, v84, v85
	v_cvt_pk_bf16_f32 v139, v86, v87
	ds_read_b64_tr_b16 v[84:85], v171 offset:25600
	ds_read_b64_tr_b16 v[86:87], v171 offset:26112
	s_waitcnt lgkmcnt(11)
	v_mfma_f32_32x32x16_bf16 v[48:63], v[104:107], v[132:135], v[48:63]
	v_add_f32_e32 v100, v90, v112
	v_add_f32_e32 v100, v91, v100
	v_add_f32_e32 v100, v92, v100
	v_add_f32_e32 v100, v93, v100
	v_cvt_pk_bf16_f32 v128, v88, v89
	v_cvt_pk_bf16_f32 v129, v90, v91
	ds_read_b64_tr_b16 v[88:89], v171 offset:29696
	ds_read_b64_tr_b16 v[90:91], v171 offset:30208
	s_waitcnt lgkmcnt(12)
	v_mfma_f32_32x32x16_bf16 v[32:47], v[108:111], v[132:135], v[32:47]
	v_add_f32_e32 v100, v94, v100
	v_add_f32_e32 v100, v95, v100
	v_add_f32_e32 v100, v64, v100
	v_add_f32_e32 v100, v65, v100
	v_cvt_pk_bf16_f32 v130, v92, v93
	v_cvt_pk_bf16_f32 v131, v94, v95
	ds_read_b64_tr_b16 v[92:93], v171 offset:26624
	ds_read_b64_tr_b16 v[94:95], v171 offset:27136
	s_waitcnt lgkmcnt(13)
	v_mfma_f32_32x32x16_bf16 v[48:63], v[144:147], v[124:127], v[48:63]
	v_add_f32_e32 v100, v66, v100
	v_add_f32_e32 v100, v67, v100
	v_add_f32_e32 v100, v68, v100
	v_add_f32_e32 v100, v69, v100
	v_cvt_pk_bf16_f32 v120, v64, v65
	v_cvt_pk_bf16_f32 v121, v66, v67
	ds_read_b64_tr_b16 v[180:181], v171 offset:30720
	ds_read_b64_tr_b16 v[182:183], v171 offset:31232
	s_waitcnt lgkmcnt(14)
	v_mfma_f32_32x32x16_bf16 v[32:47], v[148:151], v[124:127], v[32:47]
	v_add_f32_e32 v64, v70, v100
	v_add_f32_e32 v64, v71, v64
	v_add_f32_e32 v64, v72, v64
	v_add_f32_e32 v64, v73, v64
	v_cvt_pk_bf16_f32 v122, v68, v69
	v_cvt_pk_bf16_f32 v123, v70, v71
	ds_read_b64_tr_b16 v[184:185], v171 offset:27648
	ds_read_b64_tr_b16 v[186:187], v171 offset:28160
	s_waitcnt lgkmcnt(14)
	v_mfma_f32_32x32x16_bf16 v[48:63], v[172:175], v[116:119], v[48:63]
	v_add_f32_e32 v64, v74, v64
	v_add_f32_e32 v64, v75, v64
	v_add_f32_e32 v64, v76, v64
	v_add_f32_e32 v64, v77, v64
	v_cvt_pk_bf16_f32 v112, v72, v73
	v_cvt_pk_bf16_f32 v113, v74, v75
	ds_read_b64_tr_b16 v[72:73], v171 offset:31744
	ds_read_b64_tr_b16 v[74:75], v171 offset:32256
	v_mfma_f32_32x32x16_bf16 v[32:47], v[96:99], v[116:119], v[32:47]
	v_add_f32_e32 v64, v78, v64
	v_add_f32_e32 v64, v79, v64
	v_add_f32_e32 v171, 0, v64
	v_cvt_pk_bf16_f32 v114, v76, v77
	v_cvt_pk_bf16_f32 v115, v78, v79
	v_lshl_add_u64 v[64:65], v[158:159], 0, s[28:29]
	s_add_i32 s17, s57, s49
	s_mov_b32 s24, m0
	s_mov_b32 m0, s17
	s_nop 0
	global_load_lds_dwordx4 v[64:65], off
	s_mov_b32 m0, s24
	v_lshl_add_u64 v[156:157], v[156:157], 0, s[22:23]
	s_add_i32 s17, s16, s48
	s_mov_b32 s24, m0
	s_mov_b32 m0, s17
	s_nop 0
	global_load_lds_dwordx4 v[156:157], off
	s_mov_b32 m0, s24
	s_waitcnt lgkmcnt(14)
	v_mfma_f32_32x32x16_bf16 v[0:15], v[136:139], v[176:179], v[0:15]
	v_exp_f32_e32 v48, v48
	v_exp_f32_e32 v49, v49
	v_exp_f32_e32 v50, v50
	v_exp_f32_e32 v51, v51
	s_waitcnt lgkmcnt(12)
	v_mfma_f32_32x32x16_bf16 v[16:31], v[136:139], v[80:83], v[16:31]
	v_exp_f32_e32 v52, v52
	v_exp_f32_e32 v53, v53
	v_exp_f32_e32 v54, v54
	v_exp_f32_e32 v55, v55
	v_add_u32_e32 v76, s16, v165
	ds_read_b128 v[68:71], v76
	ds_read_b128 v[64:67], v76 offset:512
	s_waitcnt lgkmcnt(12)
	v_mfma_f32_32x32x16_bf16 v[0:15], v[128:131], v[84:87], v[0:15]
	v_exp_f32_e32 v56, v56
	v_exp_f32_e32 v57, v57
	v_exp_f32_e32 v58, v58
	v_exp_f32_e32 v59, v59
	ds_read_b128 v[148:151], v76 offset:2048
	ds_read_b128 v[144:147], v76 offset:2560
	s_waitcnt lgkmcnt(12)
	v_mfma_f32_32x32x16_bf16 v[16:31], v[128:131], v[88:91], v[16:31]
	v_exp_f32_e32 v60, v60
	v_exp_f32_e32 v61, v61
	v_exp_f32_e32 v62, v62
	v_exp_f32_e32 v63, v63
	ds_read_b128 v[108:111], v76 offset:4096
	ds_read_b128 v[104:107], v76 offset:4608
	s_waitcnt lgkmcnt(12)
	v_mfma_f32_32x32x16_bf16 v[0:15], v[120:123], v[92:95], v[0:15]
	v_exp_f32_e32 v32, v32
	v_exp_f32_e32 v33, v33
	v_exp_f32_e32 v34, v34
	v_exp_f32_e32 v35, v35
	ds_read_b128 v[100:103], v76 offset:6144
	ds_read_b128 v[96:99], v76 offset:6656
	s_waitcnt lgkmcnt(12)
	v_mfma_f32_32x32x16_bf16 v[16:31], v[120:123], v[180:183], v[16:31]
	v_exp_f32_e32 v36, v36
	v_exp_f32_e32 v37, v37
	v_exp_f32_e32 v38, v38
	v_exp_f32_e32 v39, v39
	s_waitcnt lgkmcnt(10)
	v_mfma_f32_32x32x16_bf16 v[0:15], v[112:115], v[184:187], v[0:15]
	v_exp_f32_e32 v40, v40
	v_exp_f32_e32 v41, v41
	v_exp_f32_e32 v42, v42
	v_exp_f32_e32 v43, v43
	s_waitcnt lgkmcnt(8)
	v_mfma_f32_32x32x16_bf16 v[16:31], v[112:115], v[72:75], v[16:31]
	v_exp_f32_e32 v44, v44
	v_exp_f32_e32 v45, v45
	v_exp_f32_e32 v46, v46
	v_exp_f32_e32 v47, v47
	s_add_i32 s17, s16, 0x2000
	s_waitcnt vmcnt(2) lgkmcnt(0)
	s_barrier
	s_cmpk_lg_i32 s16, 0x4000
	v_add_f32_e32 v72, v167, v170
	s_mov_b32 s59, s57
	s_cselect_b32 s57, s17, 0
	s_add_i32 s56, s56, 2
	v_lshl_add_u64 v[158:159], v[158:159], 0, s[22:23]
	s_mov_b32 s58, s16
	v_add_f32_e32 v167, v72, v171
	s_cmp_gt_u32 s56, 56
	s_cbranch_scc0 .LBB0_292
	s_and_b32 s17, s55, 0x3fffffc0
	s_cmp_lg_u32 0, -1
	s_cselect_b32 s16, 0, 0
	s_add_i32 s24, s16, 0x6000
	s_lshl_b32 s17, s17, 2
	v_add_u32_e32 v72, s24, v168
	s_add_i32 s24, s17, 0
	v_add3_u32 v156, v72, v166, v169
	ds_read_b64_tr_b16 v[168:169], v164 offset:32768
	ds_read_b64_tr_b16 v[170:171], v164 offset:33280
	v_add_f32_e32 v72, v48, v49
	v_add_f32_e32 v72, v50, v72
	v_add_f32_e32 v72, v51, v72
	v_add_f32_e32 v72, v52, v72
	v_add_f32_e32 v72, v53, v72
	v_cvt_pk_bf16_f32 v136, v48, v49
	v_cvt_pk_bf16_f32 v137, v50, v51
	s_waitcnt lgkmcnt(9)
	v_mfma_f32_32x32x16_bf16 v[80:95], v[68:71], v[140:143], 0
	ds_read_b64_tr_b16 v[48:49], v164 offset:36864
	ds_read_b64_tr_b16 v[50:51], v164 offset:37376
	v_add_f32_e32 v68, v54, v72
	v_add_f32_e32 v68, v55, v68
	v_add_f32_e32 v68, v56, v68
	v_add_f32_e32 v112, v57, v68
	v_cvt_pk_bf16_f32 v138, v52, v53
	v_cvt_pk_bf16_f32 v139, v54, v55
	s_waitcnt lgkmcnt(10)
	v_mfma_f32_32x32x16_bf16 v[64:79], v[64:67], v[140:143], 0
	ds_read_b64_tr_b16 v[52:53], v164 offset:33792
	ds_read_b64_tr_b16 v[54:55], v164 offset:34304
	v_add_f32_e32 v112, v58, v112
	v_add_f32_e32 v112, v59, v112
	v_add_f32_e32 v112, v60, v112
	v_add_f32_e32 v112, v61, v112
	v_cvt_pk_bf16_f32 v128, v56, v57
	v_cvt_pk_bf16_f32 v129, v58, v59
	s_waitcnt lgkmcnt(11)
	v_mfma_f32_32x32x16_bf16 v[80:95], v[148:151], v[132:135], v[80:95]
	ds_read_b64_tr_b16 v[56:57], v164 offset:37888
	ds_read_b64_tr_b16 v[58:59], v164 offset:38400
	v_add_f32_e32 v112, v62, v112
	v_add_f32_e32 v112, v63, v112
	v_add_f32_e32 v112, v32, v112
	v_add_f32_e32 v112, v33, v112
	v_cvt_pk_bf16_f32 v130, v60, v61
	v_cvt_pk_bf16_f32 v131, v62, v63
	s_waitcnt lgkmcnt(12)
	v_mfma_f32_32x32x16_bf16 v[64:79], v[144:147], v[132:135], v[64:79]
	ds_read_b64_tr_b16 v[60:61], v164 offset:34816
	ds_read_b64_tr_b16 v[62:63], v164 offset:35328
	s_waitcnt lgkmcnt(13)
	v_mfma_f32_32x32x16_bf16 v[80:95], v[108:111], v[124:127], v[80:95]
	v_add_f32_e32 v108, v34, v112
	v_add_f32_e32 v108, v35, v108
	v_add_f32_e32 v108, v36, v108
	v_add_f32_e32 v108, v37, v108
	v_cvt_pk_bf16_f32 v120, v32, v33
	v_cvt_pk_bf16_f32 v121, v34, v35
	ds_read_b64_tr_b16 v[32:33], v164 offset:38912
	ds_read_b64_tr_b16 v[34:35], v164 offset:39424
	s_waitcnt lgkmcnt(14)
	v_mfma_f32_32x32x16_bf16 v[64:79], v[104:107], v[124:127], v[64:79]
	v_add_f32_e32 v104, v38, v108
	v_add_f32_e32 v104, v39, v104
	v_add_f32_e32 v104, v40, v104
	v_add_f32_e32 v104, v41, v104
	v_cvt_pk_bf16_f32 v122, v36, v37
	v_cvt_pk_bf16_f32 v123, v38, v39
	ds_read_b64_tr_b16 v[36:37], v164 offset:35840
	ds_read_b64_tr_b16 v[38:39], v164 offset:36352
	s_waitcnt lgkmcnt(14)
	v_mfma_f32_32x32x16_bf16 v[80:95], v[100:103], v[116:119], v[80:95]
	v_add_f32_e32 v100, v42, v104
	v_add_f32_e32 v100, v43, v100
	v_add_f32_e32 v100, v44, v100
	v_add_f32_e32 v100, v45, v100
	v_cvt_pk_bf16_f32 v112, v40, v41
	v_cvt_pk_bf16_f32 v113, v42, v43
	ds_read_b64_tr_b16 v[40:41], v164 offset:39936
	ds_read_b64_tr_b16 v[42:43], v164 offset:40448
	v_mfma_f32_32x32x16_bf16 v[64:79], v[96:99], v[116:119], v[64:79]
	v_add_f32_e32 v96, v46, v100
	v_add_f32_e32 v96, v47, v96
	v_add_f32_e32 v96, 0, v96
	v_cvt_pk_bf16_f32 v114, v44, v45
	v_cvt_pk_bf16_f32 v115, v46, v47
	s_add_i32 s16, s16, s54
	v_lshl_add_u64 v[44:45], v[154:155], 0, s[66:67]
	s_add_i32 s17, s16, 0x4000
	s_mov_b32 s25, m0
	s_mov_b32 m0, s17
	s_nop 0
	global_load_lds_dwordx4 v[44:45], off
	s_mov_b32 m0, s25
	s_mov_b64 s[42:43], 0xf00000
	v_lshl_add_u64 v[44:45], v[152:153], 0, s[42:43]
	s_mov_b32 s17, m0
	s_mov_b32 m0, s48
	s_nop 0
	global_load_lds_dwordx4 v[44:45], off
	s_mov_b32 m0, s17
	v_add_f32_e32 v157, v167, v96
	s_waitcnt lgkmcnt(14)
	v_mfma_f32_32x32x16_bf16 v[0:15], v[136:139], v[168:171], v[0:15]
	v_exp_f32_e32 v80, v80
	v_exp_f32_e32 v81, v81
	v_exp_f32_e32 v82, v82
	v_exp_f32_e32 v83, v83
	s_waitcnt lgkmcnt(12)
	v_mfma_f32_32x32x16_bf16 v[16:31], v[136:139], v[48:51], v[16:31]
	v_exp_f32_e32 v84, v84
	v_exp_f32_e32 v85, v85
	v_exp_f32_e32 v86, v86
	v_exp_f32_e32 v87, v87
	ds_read_b128 v[44:47], v165
	ds_read_b128 v[144:147], v165 offset:512
	s_waitcnt lgkmcnt(12)
	v_mfma_f32_32x32x16_bf16 v[0:15], v[128:131], v[52:55], v[0:15]
	v_exp_f32_e32 v88, v88
	v_exp_f32_e32 v89, v89
	v_exp_f32_e32 v90, v90
	v_exp_f32_e32 v91, v91
	ds_read_b128 v[52:55], v165 offset:2048
	ds_read_b128 v[148:151], v165 offset:2560
	s_waitcnt lgkmcnt(12)
	v_mfma_f32_32x32x16_bf16 v[16:31], v[128:131], v[56:59], v[16:31]
	v_exp_f32_e32 v92, v92
	v_exp_f32_e32 v93, v93
	v_exp_f32_e32 v94, v94
	v_exp_f32_e32 v95, v95
	ds_read_b128 v[56:59], v165 offset:4096
	ds_read_b128 v[166:169], v165 offset:4608
	s_waitcnt lgkmcnt(12)
	v_mfma_f32_32x32x16_bf16 v[0:15], v[120:123], v[60:63], v[0:15]
	v_exp_f32_e32 v64, v64
	v_exp_f32_e32 v65, v65
	v_exp_f32_e32 v66, v66
	v_exp_f32_e32 v67, v67
	ds_read_b128 v[60:63], v165 offset:6144
	ds_read_b128 v[48:51], v165 offset:6656
	s_waitcnt lgkmcnt(12)
	v_mfma_f32_32x32x16_bf16 v[16:31], v[120:123], v[32:35], v[16:31]
	v_exp_f32_e32 v68, v68
	v_exp_f32_e32 v69, v69
	v_exp_f32_e32 v70, v70
	v_exp_f32_e32 v71, v71
	s_waitcnt lgkmcnt(10)
	v_mfma_f32_32x32x16_bf16 v[0:15], v[112:115], v[36:39], v[0:15]
	v_exp_f32_e32 v72, v72
	v_exp_f32_e32 v73, v73
	v_exp_f32_e32 v74, v74
	v_exp_f32_e32 v75, v75
	s_waitcnt lgkmcnt(8)
	v_mfma_f32_32x32x16_bf16 v[16:31], v[112:115], v[40:43], v[16:31]
	v_exp_f32_e32 v76, v76
	v_exp_f32_e32 v77, v77
	v_exp_f32_e32 v78, v78
	v_exp_f32_e32 v79, v79
	s_waitcnt vmcnt(2) lgkmcnt(0)
	s_barrier
	ds_read_b64_tr_b16 v[170:171], v164 offset:40960
	ds_read_b64_tr_b16 v[172:173], v164 offset:41472
	v_add_f32_e32 v32, v80, v81
	v_add_f32_e32 v32, v82, v32
	v_add_f32_e32 v32, v83, v32
	v_add_f32_e32 v32, v84, v32
	v_add_f32_e32 v32, v85, v32
	v_cvt_pk_bf16_f32 v136, v80, v81
	v_cvt_pk_bf16_f32 v137, v82, v83
	s_waitcnt lgkmcnt(9)
	v_mfma_f32_32x32x16_bf16 v[96:111], v[44:47], v[140:143], 0
	ds_read_b64_tr_b16 v[80:81], v164 offset:45056
	ds_read_b64_tr_b16 v[82:83], v164 offset:45568
	v_add_f32_e32 v32, v86, v32
	v_add_f32_e32 v32, v87, v32
	v_add_f32_e32 v32, v88, v32
	v_add_f32_e32 v112, v89, v32
	s_waitcnt lgkmcnt(10)
	v_mfma_f32_32x32x16_bf16 v[32:47], v[144:147], v[140:143], 0
	v_cvt_pk_bf16_f32 v138, v84, v85
	v_cvt_pk_bf16_f32 v139, v86, v87
	ds_read_b64_tr_b16 v[84:85], v164 offset:41984
	ds_read_b64_tr_b16 v[86:87], v164 offset:42496
	s_waitcnt lgkmcnt(11)
	v_mfma_f32_32x32x16_bf16 v[96:111], v[52:55], v[132:135], v[96:111]
	v_add_f32_e32 v52, v90, v112
	v_add_f32_e32 v52, v91, v52
	v_add_f32_e32 v52, v92, v52
	v_add_f32_e32 v112, v93, v52
	v_cvt_pk_bf16_f32 v128, v88, v89
	v_cvt_pk_bf16_f32 v129, v90, v91
	ds_read_b64_tr_b16 v[52:53], v164 offset:46080
	ds_read_b64_tr_b16 v[54:55], v164 offset:46592
	s_waitcnt lgkmcnt(12)
	v_mfma_f32_32x32x16_bf16 v[32:47], v[148:151], v[132:135], v[32:47]
	v_add_f32_e32 v88, v94, v112
	v_add_f32_e32 v88, v95, v88
	v_add_f32_e32 v88, v64, v88
	v_add_f32_e32 v112, v65, v88
	v_cvt_pk_bf16_f32 v130, v92, v93
	v_cvt_pk_bf16_f32 v131, v94, v95
	ds_read_b64_tr_b16 v[88:89], v164 offset:43008
	ds_read_b64_tr_b16 v[90:91], v164 offset:43520
	s_waitcnt lgkmcnt(13)
	v_mfma_f32_32x32x16_bf16 v[96:111], v[56:59], v[124:127], v[96:111]
	v_add_f32_e32 v56, v66, v112
	v_add_f32_e32 v56, v67, v56
	v_add_f32_e32 v56, v68, v56
	v_add_f32_e32 v92, v69, v56
	v_cvt_pk_bf16_f32 v120, v64, v65
	v_cvt_pk_bf16_f32 v121, v66, v67
	ds_read_b64_tr_b16 v[56:57], v164 offset:47104
	ds_read_b64_tr_b16 v[58:59], v164 offset:47616
	s_waitcnt lgkmcnt(14)
	v_mfma_f32_32x32x16_bf16 v[32:47], v[166:169], v[124:127], v[32:47]
	v_add_f32_e32 v64, v70, v92
	v_add_f32_e32 v64, v71, v64
	v_add_f32_e32 v64, v72, v64
	v_add_f32_e32 v92, v73, v64
	v_cvt_pk_bf16_f32 v122, v68, v69
	v_cvt_pk_bf16_f32 v123, v70, v71
	ds_read_b64_tr_b16 v[64:65], v164 offset:44032
	ds_read_b64_tr_b16 v[66:67], v164 offset:44544
	s_waitcnt lgkmcnt(14)
	v_mfma_f32_32x32x16_bf16 v[96:111], v[60:63], v[116:119], v[96:111]
	v_add_f32_e32 v60, v74, v92
	v_add_f32_e32 v60, v75, v60
	v_add_f32_e32 v60, v76, v60
	v_add_f32_e32 v68, v77, v60
	v_cvt_pk_bf16_f32 v112, v72, v73
	v_cvt_pk_bf16_f32 v113, v74, v75
	ds_read_b64_tr_b16 v[60:61], v164 offset:48128
	ds_read_b64_tr_b16 v[62:63], v164 offset:48640
	v_mfma_f32_32x32x16_bf16 v[32:47], v[48:51], v[116:119], v[32:47]
	v_add_f32_e32 v48, v78, v68
	v_add_f32_e32 v48, v79, v48
	v_add_f32_e32 v48, 0, v48
	v_cvt_pk_bf16_f32 v114, v76, v77
	v_cvt_pk_bf16_f32 v115, v78, v79
	s_mov_b64 s[42:43], 0xfc0000
	v_add_f32_e32 v157, v157, v48
	v_lshl_add_u64 v[48:49], v[154:155], 0, s[42:43]
	s_mov_b32 s17, m0
	s_mov_b32 m0, s49
	s_nop 0
	global_load_lds_dwordx4 v[48:49], off
	s_mov_b32 m0, s17
	s_mov_b64 s[54:55], 0xf40000
	v_lshl_add_u64 v[48:49], v[152:153], 0, s[54:55]
	s_add_i32 s17, s16, 0x8000
	s_mov_b32 s25, m0
	s_mov_b32 m0, s17
	s_nop 0
	global_load_lds_dwordx4 v[48:49], off
	s_mov_b32 m0, s25
	s_waitcnt lgkmcnt(14)
	v_mfma_f32_32x32x16_bf16 v[0:15], v[136:139], v[170:173], v[0:15]
	v_exp_f32_e32 v96, v96
	v_exp_f32_e32 v97, v97
	v_exp_f32_e32 v98, v98
	v_exp_f32_e32 v99, v99
	s_waitcnt lgkmcnt(12)
	v_mfma_f32_32x32x16_bf16 v[16:31], v[136:139], v[80:83], v[16:31]
	v_exp_f32_e32 v100, v100
	v_exp_f32_e32 v101, v101
	v_exp_f32_e32 v102, v102
	v_exp_f32_e32 v103, v103
	ds_read_b128 v[48:51], v165 offset:8192
	ds_read_b128 v[92:95], v165 offset:8704
	s_waitcnt lgkmcnt(12)
	v_mfma_f32_32x32x16_bf16 v[0:15], v[128:131], v[84:87], v[0:15]
	v_exp_f32_e32 v104, v104
	v_exp_f32_e32 v105, v105
	v_exp_f32_e32 v106, v106
	v_exp_f32_e32 v107, v107
	ds_read_b128 v[84:87], v165 offset:10240
	ds_read_b128 v[144:147], v165 offset:10752
	s_waitcnt lgkmcnt(12)
	v_mfma_f32_32x32x16_bf16 v[16:31], v[128:131], v[52:55], v[16:31]
	v_exp_f32_e32 v108, v108
	v_exp_f32_e32 v109, v109
	v_exp_f32_e32 v110, v110
	v_exp_f32_e32 v111, v111
	ds_read_b128 v[148:151], v165 offset:12288
	ds_read_b128 v[166:169], v165 offset:12800
	s_waitcnt lgkmcnt(12)
	v_mfma_f32_32x32x16_bf16 v[0:15], v[120:123], v[88:91], v[0:15]
	v_exp_f32_e32 v32, v32
	v_exp_f32_e32 v33, v33
	v_exp_f32_e32 v34, v34
	v_exp_f32_e32 v35, v35
	ds_read_b128 v[88:91], v165 offset:14336
	ds_read_b128 v[80:83], v165 offset:14848
	s_waitcnt lgkmcnt(12)
	v_mfma_f32_32x32x16_bf16 v[16:31], v[120:123], v[56:59], v[16:31]
	v_exp_f32_e32 v36, v36
	v_exp_f32_e32 v37, v37
	v_exp_f32_e32 v38, v38
	v_exp_f32_e32 v39, v39
	s_waitcnt lgkmcnt(10)
	v_mfma_f32_32x32x16_bf16 v[0:15], v[112:115], v[64:67], v[0:15]
	v_exp_f32_e32 v40, v40
	v_exp_f32_e32 v41, v41
	v_exp_f32_e32 v42, v42
	v_exp_f32_e32 v43, v43
	s_waitcnt lgkmcnt(8)
	v_mfma_f32_32x32x16_bf16 v[16:31], v[112:115], v[60:63], v[16:31]
	v_exp_f32_e32 v44, v44
	v_exp_f32_e32 v45, v45
	v_exp_f32_e32 v46, v46
	v_exp_f32_e32 v47, v47
	s_waitcnt vmcnt(2) lgkmcnt(0)
	s_barrier
	ds_read_b64_tr_b16 v[170:171], v164 offset:24576
	ds_read_b64_tr_b16 v[172:173], v164 offset:25088
	v_add_f32_e32 v52, v96, v97
	v_add_f32_e32 v52, v98, v52
	v_add_f32_e32 v52, v99, v52
	v_add_f32_e32 v52, v100, v52
	v_add_f32_e32 v52, v101, v52
	v_cvt_pk_bf16_f32 v136, v96, v97
	v_cvt_pk_bf16_f32 v137, v98, v99
	s_waitcnt lgkmcnt(9)
	v_mfma_f32_32x32x16_bf16 v[64:79], v[48:51], v[140:143], 0
	ds_read_b64_tr_b16 v[96:97], v164 offset:28672
	ds_read_b64_tr_b16 v[98:99], v164 offset:29184
	v_add_f32_e32 v48, v102, v52
	v_add_f32_e32 v48, v103, v48
	v_add_f32_e32 v48, v104, v48
	v_add_f32_e32 v112, v105, v48
	v_cvt_pk_bf16_f32 v138, v100, v101
	v_cvt_pk_bf16_f32 v139, v102, v103
	s_waitcnt lgkmcnt(10)
	v_mfma_f32_32x32x16_bf16 v[48:63], v[92:95], v[140:143], 0
	ds_read_b64_tr_b16 v[92:93], v164 offset:25600
	ds_read_b64_tr_b16 v[94:95], v164 offset:26112
	s_waitcnt lgkmcnt(11)
	v_mfma_f32_32x32x16_bf16 v[64:79], v[84:87], v[132:135], v[64:79]
	v_add_f32_e32 v84, v106, v112
	v_add_f32_e32 v84, v107, v84
	v_add_f32_e32 v84, v108, v84
	v_add_f32_e32 v100, v109, v84
	v_cvt_pk_bf16_f32 v128, v104, v105
	v_cvt_pk_bf16_f32 v129, v106, v107
	ds_read_b64_tr_b16 v[84:85], v164 offset:29696
	ds_read_b64_tr_b16 v[86:87], v164 offset:30208
	v_add_f32_e32 v100, v110, v100
	v_add_f32_e32 v100, v111, v100
	v_add_f32_e32 v100, v32, v100
	v_add_f32_e32 v104, v33, v100
	v_cvt_pk_bf16_f32 v130, v108, v109
	v_cvt_pk_bf16_f32 v131, v110, v111
	s_waitcnt lgkmcnt(12)
	v_mfma_f32_32x32x16_bf16 v[48:63], v[144:147], v[132:135], v[48:63]
	ds_read_b64_tr_b16 v[100:101], v164 offset:26624
	ds_read_b64_tr_b16 v[102:103], v164 offset:27136
	v_add_f32_e32 v104, v34, v104
	v_add_f32_e32 v104, v35, v104
	v_add_f32_e32 v104, v36, v104
	v_add_f32_e32 v104, v37, v104
	v_cvt_pk_bf16_f32 v120, v32, v33
	v_cvt_pk_bf16_f32 v121, v34, v35
	s_waitcnt lgkmcnt(13)
	v_mfma_f32_32x32x16_bf16 v[64:79], v[148:151], v[124:127], v[64:79]
	ds_read_b64_tr_b16 v[32:33], v164 offset:30720
	ds_read_b64_tr_b16 v[34:35], v164 offset:31232
	v_add_f32_e32 v104, v38, v104
	v_add_f32_e32 v104, v39, v104
	v_add_f32_e32 v104, v40, v104
	v_add_f32_e32 v104, v41, v104
	v_cvt_pk_bf16_f32 v122, v36, v37
	v_cvt_pk_bf16_f32 v123, v38, v39
	s_waitcnt lgkmcnt(14)
	v_mfma_f32_32x32x16_bf16 v[48:63], v[166:169], v[124:127], v[48:63]
	ds_read_b64_tr_b16 v[36:37], v164 offset:27648
	ds_read_b64_tr_b16 v[38:39], v164 offset:28160
	s_waitcnt lgkmcnt(14)
	v_mfma_f32_32x32x16_bf16 v[64:79], v[88:91], v[116:119], v[64:79]
	v_add_f32_e32 v88, v42, v104
	v_add_f32_e32 v88, v43, v88
	v_add_f32_e32 v88, v44, v88
	v_add_f32_e32 v88, v45, v88
	v_cvt_pk_bf16_f32 v112, v40, v41
	v_cvt_pk_bf16_f32 v113, v42, v43
	ds_read_b64_tr_b16 v[40:41], v164 offset:31744
	ds_read_b64_tr_b16 v[42:43], v164 offset:32256
	v_mfma_f32_32x32x16_bf16 v[48:63], v[80:83], v[116:119], v[48:63]
	v_add_f32_e32 v80, v46, v88
	v_add_f32_e32 v80, v47, v80
	v_add_f32_e32 v80, 0, v80
	v_cvt_pk_bf16_f32 v114, v44, v45
	v_cvt_pk_bf16_f32 v115, v46, v47
	v_lshl_add_u64 v[44:45], v[152:153], 0, s[66:67]
	s_add_i32 s16, s16, 0xa000
	s_mov_b32 s17, m0
	s_mov_b32 m0, s16
	s_nop 0
	global_load_lds_dwordx4 v[44:45], off
	s_mov_b32 m0, s17
	v_add_f32_e32 v154, v157, v80
	s_waitcnt lgkmcnt(14)
	v_mfma_f32_32x32x16_bf16 v[0:15], v[136:139], v[170:173], v[0:15]
	v_exp_f32_e32 v64, v64
	v_exp_f32_e32 v65, v65
	v_exp_f32_e32 v66, v66
	v_exp_f32_e32 v67, v67
	s_waitcnt lgkmcnt(12)
	v_mfma_f32_32x32x16_bf16 v[16:31], v[136:139], v[96:99], v[16:31]
	v_exp_f32_e32 v68, v68
	v_exp_f32_e32 v69, v69
	v_exp_f32_e32 v70, v70
	v_exp_f32_e32 v71, v71
	ds_read_b128 v[44:47], v165 offset:16384
	ds_read_b128 v[104:107], v165 offset:16896
	s_waitcnt lgkmcnt(12)
	v_mfma_f32_32x32x16_bf16 v[0:15], v[128:131], v[92:95], v[0:15]
	v_exp_f32_e32 v72, v72
	v_exp_f32_e32 v73, v73
	v_exp_f32_e32 v74, v74
	v_exp_f32_e32 v75, v75
	ds_read_b128 v[108:111], v165 offset:18432
	ds_read_b128 v[144:147], v165 offset:18944
	s_waitcnt lgkmcnt(12)
	v_mfma_f32_32x32x16_bf16 v[16:31], v[128:131], v[84:87], v[16:31]
	v_exp_f32_e32 v76, v76
	v_exp_f32_e32 v77, v77
	v_exp_f32_e32 v78, v78
	v_exp_f32_e32 v79, v79
	ds_read_b128 v[148:151], v165 offset:20480
	ds_read_b128 v[166:169], v165 offset:20992
	s_waitcnt lgkmcnt(12)
	v_mfma_f32_32x32x16_bf16 v[0:15], v[120:123], v[100:103], v[0:15]
	v_exp_f32_e32 v48, v48
	v_exp_f32_e32 v49, v49
	v_exp_f32_e32 v50, v50
	v_exp_f32_e32 v51, v51
	ds_read_b128 v[100:103], v165 offset:22528
	ds_read_b128 v[96:99], v165 offset:23040
	s_waitcnt lgkmcnt(12)
	v_mfma_f32_32x32x16_bf16 v[16:31], v[120:123], v[32:35], v[16:31]
	v_exp_f32_e32 v52, v52
	v_exp_f32_e32 v53, v53
	v_exp_f32_e32 v54, v54
	v_exp_f32_e32 v55, v55
	s_waitcnt lgkmcnt(10)
	v_mfma_f32_32x32x16_bf16 v[0:15], v[112:115], v[36:39], v[0:15]
	v_exp_f32_e32 v56, v56
	v_exp_f32_e32 v57, v57
	v_exp_f32_e32 v58, v58
	v_exp_f32_e32 v59, v59
	s_waitcnt lgkmcnt(8)
	v_mfma_f32_32x32x16_bf16 v[16:31], v[112:115], v[40:43], v[16:31]
	v_exp_f32_e32 v60, v60
	v_exp_f32_e32 v61, v61
	v_exp_f32_e32 v62, v62
	v_exp_f32_e32 v63, v63
	s_waitcnt vmcnt(1) lgkmcnt(0)
	s_barrier
	ds_read_b64_tr_b16 v[170:171], v164 offset:32768
	ds_read_b64_tr_b16 v[172:173], v164 offset:33280
	v_add_f32_e32 v32, v64, v65
	v_add_f32_e32 v32, v66, v32
	v_add_f32_e32 v32, v67, v32
	v_add_f32_e32 v32, v68, v32
	v_add_f32_e32 v32, v69, v32
	v_cvt_pk_bf16_f32 v136, v64, v65
	v_cvt_pk_bf16_f32 v137, v66, v67
	s_waitcnt lgkmcnt(9)
	v_mfma_f32_32x32x16_bf16 v[80:95], v[44:47], v[140:143], 0
	ds_read_b64_tr_b16 v[64:65], v164 offset:36864
	ds_read_b64_tr_b16 v[66:67], v164 offset:37376
	v_add_f32_e32 v32, v70, v32
	v_add_f32_e32 v32, v71, v32
	v_add_f32_e32 v32, v72, v32
	v_add_f32_e32 v112, v73, v32
	s_waitcnt lgkmcnt(10)
	v_mfma_f32_32x32x16_bf16 v[32:47], v[104:107], v[140:143], 0
	v_cvt_pk_bf16_f32 v138, v68, v69
	v_cvt_pk_bf16_f32 v139, v70, v71
	ds_read_b64_tr_b16 v[68:69], v164 offset:33792
	ds_read_b64_tr_b16 v[70:71], v164 offset:34304
	v_add_f32_e32 v104, v74, v112
	v_add_f32_e32 v104, v75, v104
	v_add_f32_e32 v104, v76, v104
	v_add_f32_e32 v104, v77, v104
	v_cvt_pk_bf16_f32 v128, v72, v73
	v_cvt_pk_bf16_f32 v129, v74, v75
	s_waitcnt lgkmcnt(11)
	v_mfma_f32_32x32x16_bf16 v[80:95], v[108:111], v[132:135], v[80:95]
	ds_read_b64_tr_b16 v[72:73], v164 offset:37888
	ds_read_b64_tr_b16 v[74:75], v164 offset:38400
	s_waitcnt lgkmcnt(12)
	v_mfma_f32_32x32x16_bf16 v[32:47], v[144:147], v[132:135], v[32:47]
	v_add_f32_e32 v104, v78, v104
	v_add_f32_e32 v104, v79, v104
	v_add_f32_e32 v104, v48, v104
	v_add_f32_e32 v104, v49, v104
	v_cvt_pk_bf16_f32 v130, v76, v77
	v_cvt_pk_bf16_f32 v131, v78, v79
	ds_read_b64_tr_b16 v[76:77], v164 offset:34816
	ds_read_b64_tr_b16 v[78:79], v164 offset:35328
	v_add_f32_e32 v104, v50, v104
	v_add_f32_e32 v104, v51, v104
	v_add_f32_e32 v104, v52, v104
	v_add_f32_e32 v104, v53, v104
	v_cvt_pk_bf16_f32 v120, v48, v49
	v_cvt_pk_bf16_f32 v121, v50, v51
	s_waitcnt lgkmcnt(13)
	v_mfma_f32_32x32x16_bf16 v[80:95], v[148:151], v[124:127], v[80:95]
	ds_read_b64_tr_b16 v[48:49], v164 offset:38912
	ds_read_b64_tr_b16 v[50:51], v164 offset:39424
	s_waitcnt lgkmcnt(14)
	v_mfma_f32_32x32x16_bf16 v[32:47], v[166:169], v[124:127], v[32:47]
	v_add_f32_e32 v104, v54, v104
	v_add_f32_e32 v104, v55, v104
	v_add_f32_e32 v104, v56, v104
	v_add_f32_e32 v104, v57, v104
	v_cvt_pk_bf16_f32 v122, v52, v53
	v_cvt_pk_bf16_f32 v123, v54, v55
	ds_read_b64_tr_b16 v[52:53], v164 offset:35840
	ds_read_b64_tr_b16 v[54:55], v164 offset:36352
	s_waitcnt lgkmcnt(14)
	v_mfma_f32_32x32x16_bf16 v[80:95], v[100:103], v[116:119], v[80:95]
	v_add_f32_e32 v100, v58, v104
	v_add_f32_e32 v100, v59, v100
	v_add_f32_e32 v100, v60, v100
	v_add_f32_e32 v100, v61, v100
	v_cvt_pk_bf16_f32 v112, v56, v57
	v_cvt_pk_bf16_f32 v113, v58, v59
	ds_read_b64_tr_b16 v[56:57], v164 offset:39936
	ds_read_b64_tr_b16 v[58:59], v164 offset:40448
	v_mfma_f32_32x32x16_bf16 v[32:47], v[96:99], v[116:119], v[32:47]
	v_add_f32_e32 v96, v62, v100
	v_add_f32_e32 v96, v63, v96
	v_add_f32_e32 v96, 0, v96
	v_cvt_pk_bf16_f32 v114, v60, v61
	v_cvt_pk_bf16_f32 v115, v62, v63
	v_lshl_add_u64 v[60:61], v[152:153], 0, s[42:43]
	s_mov_b32 s16, m0
	s_mov_b32 m0, s48
	s_nop 0
	global_load_lds_dwordx4 v[60:61], off
	s_mov_b32 m0, s16
	v_add_f32_e32 v100, v154, v96
	s_waitcnt lgkmcnt(14)
	v_mfma_f32_32x32x16_bf16 v[0:15], v[136:139], v[170:173], v[0:15]
	v_exp_f32_e32 v80, v80
	v_exp_f32_e32 v81, v81
	v_exp_f32_e32 v82, v82
	v_exp_f32_e32 v83, v83
	s_waitcnt lgkmcnt(12)
	v_mfma_f32_32x32x16_bf16 v[16:31], v[136:139], v[64:67], v[16:31]
	v_exp_f32_e32 v84, v84
	v_exp_f32_e32 v85, v85
	v_exp_f32_e32 v86, v86
	v_exp_f32_e32 v87, v87
	ds_read_b128 v[60:63], v165
	ds_read_b128 v[64:67], v165 offset:512
	s_waitcnt lgkmcnt(12)
	v_mfma_f32_32x32x16_bf16 v[0:15], v[128:131], v[68:71], v[0:15]
	v_exp_f32_e32 v88, v88
	v_exp_f32_e32 v89, v89
	v_exp_f32_e32 v90, v90
	v_exp_f32_e32 v91, v91
	ds_read_b128 v[102:105], v165 offset:2048
	ds_read_b128 v[106:109], v165 offset:2560
	s_waitcnt lgkmcnt(12)
	v_mfma_f32_32x32x16_bf16 v[16:31], v[128:131], v[72:75], v[16:31]
	v_exp_f32_e32 v92, v92
	v_exp_f32_e32 v93, v93
	v_exp_f32_e32 v94, v94
	v_exp_f32_e32 v95, v95
	ds_read_b128 v[144:147], v165 offset:4096
	ds_read_b128 v[148:151], v165 offset:4608
	s_waitcnt lgkmcnt(12)
	v_mfma_f32_32x32x16_bf16 v[0:15], v[120:123], v[76:79], v[0:15]
	v_exp_f32_e32 v32, v32
	v_exp_f32_e32 v33, v33
	v_exp_f32_e32 v34, v34
	v_exp_f32_e32 v35, v35
	ds_read_b128 v[152:155], v165 offset:6144
	ds_read_b128 v[96:99], v165 offset:6656
	s_waitcnt lgkmcnt(12)
	v_mfma_f32_32x32x16_bf16 v[16:31], v[120:123], v[48:51], v[16:31]
	v_exp_f32_e32 v36, v36
	v_exp_f32_e32 v37, v37
	v_exp_f32_e32 v38, v38
	v_exp_f32_e32 v39, v39
	s_waitcnt lgkmcnt(10)
	v_mfma_f32_32x32x16_bf16 v[0:15], v[112:115], v[52:55], v[0:15]
	v_exp_f32_e32 v40, v40
	v_exp_f32_e32 v41, v41
	v_exp_f32_e32 v42, v42
	v_exp_f32_e32 v43, v43
	s_waitcnt lgkmcnt(8)
	v_mfma_f32_32x32x16_bf16 v[16:31], v[112:115], v[56:59], v[16:31]
	v_exp_f32_e32 v44, v44
	v_exp_f32_e32 v45, v45
	v_exp_f32_e32 v46, v46
	v_exp_f32_e32 v47, v47
	s_waitcnt vmcnt(0) lgkmcnt(0)
	s_barrier
	s_mov_b32 s78, 0
	s_cmp_lg_u32 s3, 0x100
	s_cbranch_scc1 .Lgqa_nopf
	s_add_i32 s79, s19, s3
	s_cmpk_gt_i32 s79, 0x9ff
	s_cbranch_scc1 .Lgqa_nopf
	s_add_u32 s80, s76, 0x2000000
	s_addc_u32 s81, s77, 0
	v_lshlrev_b32_e32 v212, 12, v162
	v_lshl_or_b32 v212, v163, 4, v212
	global_load_dwordx4 v[196:199], v212, s[80:81] offset:1536
	global_load_dwordx4 v[200:203], v212, s[80:81] offset:1568
	global_load_dwordx4 v[204:207], v212, s[80:81] offset:1600
	global_load_dwordx4 v[208:211], v212, s[80:81] offset:1632
	s_mov_b32 s78, 1
.Lgqa_nopf:
	ds_read_b64_tr_b16 v[166:167], v164 offset:40960
	ds_read_b64_tr_b16 v[168:169], v164 offset:41472
	v_add_f32_e32 v48, v80, v81
	v_add_f32_e32 v48, v82, v48
	v_add_f32_e32 v48, v83, v48
	v_add_f32_e32 v48, v84, v48
	v_add_f32_e32 v68, v85, v48
	v_cvt_pk_bf16_f32 v136, v80, v81
	v_cvt_pk_bf16_f32 v137, v82, v83
	s_waitcnt lgkmcnt(9)
	v_mfma_f32_32x32x16_bf16 v[48:63], v[60:63], v[140:143], 0
	ds_read_b64_tr_b16 v[80:81], v164 offset:45056
	ds_read_b64_tr_b16 v[82:83], v164 offset:45568
	v_add_f32_e32 v68, v86, v68
	v_add_f32_e32 v68, v87, v68
	v_add_f32_e32 v68, v88, v68
	v_add_f32_e32 v101, v89, v68
	v_cvt_pk_bf16_f32 v138, v84, v85
	v_cvt_pk_bf16_f32 v139, v86, v87
	s_waitcnt lgkmcnt(10)
	v_mfma_f32_32x32x16_bf16 v[64:79], v[64:67], v[140:143], 0
	ds_read_b64_tr_b16 v[84:85], v164 offset:41984
	ds_read_b64_tr_b16 v[86:87], v164 offset:42496
	v_add_f32_e32 v101, v90, v101
	v_add_f32_e32 v101, v91, v101
	v_add_f32_e32 v101, v92, v101
	v_add_f32_e32 v101, v93, v101
	v_cvt_pk_bf16_f32 v128, v88, v89
	v_cvt_pk_bf16_f32 v129, v90, v91
	s_waitcnt lgkmcnt(11)
	v_mfma_f32_32x32x16_bf16 v[48:63], v[102:105], v[132:135], v[48:63]
	ds_read_b64_tr_b16 v[88:89], v164 offset:46080
	ds_read_b64_tr_b16 v[90:91], v164 offset:46592
	v_add_f32_e32 v101, v94, v101
	v_add_f32_e32 v101, v95, v101
	v_add_f32_e32 v101, v32, v101
	v_add_f32_e32 v101, v33, v101
	v_cvt_pk_bf16_f32 v130, v92, v93
	v_cvt_pk_bf16_f32 v131, v94, v95
	s_waitcnt lgkmcnt(12)
	v_mfma_f32_32x32x16_bf16 v[64:79], v[106:109], v[132:135], v[64:79]
	ds_read_b64_tr_b16 v[92:93], v164 offset:43008
	ds_read_b64_tr_b16 v[94:95], v164 offset:43520
	v_add_f32_e32 v101, v34, v101
	v_add_f32_e32 v101, v35, v101
	v_add_f32_e32 v101, v36, v101
	v_add_f32_e32 v101, v37, v101
	v_cvt_pk_bf16_f32 v120, v32, v33
	v_cvt_pk_bf16_f32 v121, v34, v35
	s_waitcnt lgkmcnt(13)
	v_mfma_f32_32x32x16_bf16 v[48:63], v[144:147], v[124:127], v[48:63]
	ds_read_b64_tr_b16 v[32:33], v164 offset:47104
	ds_read_b64_tr_b16 v[34:35], v164 offset:47616
	v_add_f32_e32 v101, v38, v101
	v_add_f32_e32 v101, v39, v101
	v_add_f32_e32 v101, v40, v101
	v_add_f32_e32 v101, v41, v101
	v_cvt_pk_bf16_f32 v122, v36, v37
	v_cvt_pk_bf16_f32 v123, v38, v39
	s_waitcnt lgkmcnt(14)
	v_mfma_f32_32x32x16_bf16 v[64:79], v[148:151], v[124:127], v[64:79]
	ds_read_b64_tr_b16 v[36:37], v164 offset:44032
	ds_read_b64_tr_b16 v[38:39], v164 offset:44544
	v_add_f32_e32 v101, v42, v101
	v_add_f32_e32 v101, v43, v101
	v_add_f32_e32 v101, v44, v101
	v_add_f32_e32 v101, v45, v101
	v_cvt_pk_bf16_f32 v112, v40, v41
	v_cvt_pk_bf16_f32 v113, v42, v43
	s_waitcnt lgkmcnt(14)
	v_mfma_f32_32x32x16_bf16 v[48:63], v[152:155], v[116:119], v[48:63]
	ds_read_b64_tr_b16 v[40:41], v164 offset:48128
	ds_read_b64_tr_b16 v[42:43], v164 offset:48640
	v_mfma_f32_32x32x16_bf16 v[64:79], v[96:99], v[116:119], v[64:79]
	v_add_f32_e32 v96, v46, v101
	v_add_f32_e32 v96, v47, v96
	v_add_f32_e32 v96, 0, v96
	v_cvt_pk_bf16_f32 v114, v44, v45
	v_cvt_pk_bf16_f32 v115, v46, v47
	s_waitcnt lgkmcnt(14)
	v_mfma_f32_32x32x16_bf16 v[0:15], v[136:139], v[166:169], v[0:15]
	s_nop 1
	v_exp_f32_e32 v48, v48
	v_exp_f32_e32 v49, v49
	v_exp_f32_e32 v50, v50
	v_exp_f32_e32 v51, v51
	s_waitcnt lgkmcnt(12)
	v_mfma_f32_32x32x16_bf16 v[16:31], v[136:139], v[80:83], v[16:31]
	v_exp_f32_e32 v52, v52
	v_exp_f32_e32 v53, v53
	v_exp_f32_e32 v54, v54
	v_exp_f32_e32 v55, v55
	s_waitcnt lgkmcnt(10)
	v_mfma_f32_32x32x16_bf16 v[0:15], v[128:131], v[84:87], v[0:15]
	v_exp_f32_e32 v56, v56
	v_exp_f32_e32 v57, v57
	v_exp_f32_e32 v58, v58
	v_exp_f32_e32 v59, v59
	s_waitcnt lgkmcnt(8)
	v_mfma_f32_32x32x16_bf16 v[16:31], v[128:131], v[88:91], v[16:31]
	v_exp_f32_e32 v60, v60
	v_exp_f32_e32 v61, v61
	v_exp_f32_e32 v62, v62
	v_exp_f32_e32 v63, v63
	s_waitcnt lgkmcnt(6)
	v_mfma_f32_32x32x16_bf16 v[0:15], v[120:123], v[92:95], v[0:15]
	v_exp_f32_e32 v64, v64
	v_exp_f32_e32 v65, v65
	v_exp_f32_e32 v66, v66
	v_exp_f32_e32 v67, v67
	s_waitcnt lgkmcnt(4)
	v_mfma_f32_32x32x16_bf16 v[16:31], v[120:123], v[32:35], v[16:31]
	v_exp_f32_e32 v68, v68
	v_exp_f32_e32 v69, v69
	v_exp_f32_e32 v70, v70
	v_exp_f32_e32 v71, v71
	s_waitcnt lgkmcnt(2)
	v_mfma_f32_32x32x16_bf16 v[0:15], v[112:115], v[36:39], v[0:15]
	v_exp_f32_e32 v72, v72
	v_exp_f32_e32 v73, v73
	v_exp_f32_e32 v74, v74
	v_exp_f32_e32 v75, v75
	s_waitcnt lgkmcnt(0)
	v_mfma_f32_32x32x16_bf16 v[16:31], v[112:115], v[40:43], v[16:31]
	v_exp_f32_e32 v76, v76
	v_exp_f32_e32 v77, v77
	v_exp_f32_e32 v78, v78
	v_exp_f32_e32 v79, v79
	v_add_f32_e32 v32, v48, v49
	v_add_f32_e32 v32, v50, v32
	v_add_f32_e32 v32, v51, v32
	v_add_f32_e32 v32, v52, v32
	v_add_f32_e32 v32, v53, v32
	v_add_f32_e32 v32, v54, v32
	v_add_f32_e32 v32, v55, v32
	v_add_f32_e32 v32, v56, v32
	v_add_f32_e32 v32, v57, v32
	v_add_f32_e32 v32, v58, v32
	v_add_f32_e32 v32, v59, v32
	v_add_f32_e32 v32, v60, v32
	v_add_f32_e32 v32, v61, v32
	v_add_f32_e32 v32, v62, v32
	v_add_f32_e32 v32, v63, v32
	v_add_f32_e32 v32, v64, v32
	v_add_f32_e32 v32, v65, v32
	v_add_f32_e32 v32, v66, v32
	v_add_f32_e32 v32, v67, v32
	v_add_f32_e32 v32, v68, v32
	v_add_f32_e32 v32, v69, v32
	v_add_f32_e32 v32, v70, v32
	v_add_f32_e32 v32, v71, v32
	v_add_f32_e32 v32, v72, v32
	v_add_f32_e32 v32, v73, v32
	v_add_f32_e32 v32, v74, v32
	v_add_f32_e32 v32, v75, v32
	v_add_f32_e32 v32, v76, v32
	v_add_f32_e32 v32, v77, v32
	v_add_f32_e32 v32, v78, v32
	v_add_f32_e32 v32, v79, v32
	v_add_f32_e32 v33, v100, v96
	v_add_f32_e32 v32, v33, v32
	v_cvt_pk_bf16_f32 v34, v48, v49
	v_cvt_pk_bf16_f32 v35, v50, v51
	v_cvt_pk_bf16_f32 v36, v52, v53
	v_cvt_pk_bf16_f32 v37, v54, v55
	v_cvt_pk_bf16_f32 v38, v56, v57
	v_cvt_pk_bf16_f32 v39, v58, v59
	v_cvt_pk_bf16_f32 v40, v60, v61
	v_cvt_pk_bf16_f32 v41, v62, v63
	v_cvt_pk_bf16_f32 v42, v64, v65
	v_cvt_pk_bf16_f32 v43, v66, v67
	v_cvt_pk_bf16_f32 v44, v68, v69
	v_cvt_pk_bf16_f32 v45, v70, v71
	v_cvt_pk_bf16_f32 v46, v72, v73
	v_cvt_pk_bf16_f32 v47, v74, v75
	v_cvt_pk_bf16_f32 v48, v76, v77
	v_cvt_pk_bf16_f32 v49, v78, v79
	ds_read_b64_tr_b16 v[50:51],v156 offset:0
	ds_read_b64_tr_b16 v[52:53],v156 offset:512
	ds_read_b64_tr_b16 v[54:55],v156 offset:1024
	ds_read_b64_tr_b16 v[56:57],v156 offset:1536
	ds_read_b64_tr_b16 v[58:59],v156 offset:2048
	ds_read_b64_tr_b16 v[60:61],v156 offset:2560
	ds_read_b64_tr_b16 v[62:63],v156 offset:3072
	ds_read_b64_tr_b16 v[64:65],v156 offset:3584
	s_waitcnt lgkmcnt(0)
	s_nop 0
	v_mfma_f32_32x32x16_bf16 v[0:15], v[34:37], v[50:53], v[0:15]
	ds_read_b64_tr_b16 v[50:51],v156 offset:4096
	ds_read_b64_tr_b16 v[52:53],v156 offset:4608
	v_mfma_f32_32x32x16_bf16 v[0:15], v[38:41], v[54:57], v[0:15]
	ds_read_b64_tr_b16 v[54:55],v156 offset:5120
	ds_read_b64_tr_b16 v[56:57],v156 offset:5632
	v_mfma_f32_32x32x16_bf16 v[0:15], v[42:45], v[58:61], v[0:15]
	ds_read_b64_tr_b16 v[58:59],v156 offset:6144
	ds_read_b64_tr_b16 v[60:61],v156 offset:6656
	v_mfma_f32_32x32x16_bf16 v[0:15], v[46:49], v[62:65], v[0:15]
	ds_read_b64_tr_b16 v[62:63],v156 offset:7168
	ds_read_b64_tr_b16 v[64:65],v156 offset:7680
	s_waitcnt lgkmcnt(0)
	v_mfma_f32_32x32x16_bf16 v[16:31], v[34:37], v[50:53], v[16:31]
	v_mov_b32_e32 v33, v32
	s_nop 1
	v_permlane32_swap_b32_e32 v32, v33
	v_cmp_gt_u32_e32 vcc, 32, v160
	v_mfma_f32_32x32x16_bf16 v[16:31], v[38:41], v[54:57], v[16:31]
	v_mfma_f32_32x32x16_bf16 v[16:31], v[42:45], v[58:61], v[16:31]
	v_mfma_f32_32x32x16_bf16 v[16:31], v[46:49], v[62:65], v[16:31]
	s_and_saveexec_b64 s[16:17], vcc
	s_cbranch_execz .LBB0_290
	v_lshl_add_u32 v34, v162, 2, s24
	v_add_f32_e32 v32, v32, v33
	ds_write_b32 v34, v32 offset:49280
	s_branch .LBB0_290

.LBB0_412:
	v_ashrrev_i32_e32 v3, 31, v2
	v_lshl_add_u64 v[20:21], v[2:3], 2, s[16:17]
	global_load_dword v24, v[20:21], off
	global_load_dwordx2 v[56:57], v[4:5], off
	global_load_dwordx2 v[88:89], v[6:7], off
	global_load_dword v40, v[20:21], off offset:64
	global_load_dword v25, v[20:21], off offset:128
	global_load_dwordx2 v[58:59], v[4:5], off offset:8
	global_load_dwordx2 v[90:91], v[6:7], off offset:8
	global_load_dword v41, v[20:21], off offset:192
	global_load_dword v26, v[20:21], off offset:256
	global_load_dwordx2 v[60:61], v[4:5], off offset:16
	global_load_dwordx2 v[92:93], v[6:7], off offset:16
	global_load_dword v42, v[20:21], off offset:320
	global_load_dword v27, v[20:21], off offset:384
	global_load_dwordx2 v[62:63], v[4:5], off offset:24
	global_load_dwordx2 v[94:95], v[6:7], off offset:24
	global_load_dword v43, v[20:21], off offset:448
	global_load_dword v28, v[20:21], off offset:512
	global_load_dwordx2 v[64:65], v[4:5], off offset:32
	global_load_dwordx2 v[96:97], v[6:7], off offset:32
	global_load_dword v44, v[20:21], off offset:576
	global_load_dword v29, v[20:21], off offset:640
	global_load_dwordx2 v[66:67], v[4:5], off offset:40
	global_load_dwordx2 v[98:99], v[6:7], off offset:40
	global_load_dword v45, v[20:21], off offset:704
	global_load_dword v30, v[20:21], off offset:768
	global_load_dwordx2 v[68:69], v[4:5], off offset:48
	global_load_dwordx2 v[100:101], v[6:7], off offset:48
	global_load_dword v46, v[20:21], off offset:832
	global_load_dword v31, v[20:21], off offset:896
	global_load_dwordx2 v[70:71], v[4:5], off offset:56
	global_load_dwordx2 v[102:103], v[6:7], off offset:56
	global_load_dword v47, v[20:21], off offset:960
	global_load_dword v32, v[20:21], off offset:1024
	global_load_dwordx2 v[72:73], v[4:5], off offset:64
	global_load_dwordx2 v[104:105], v[6:7], off offset:64
	global_load_dword v48, v[20:21], off offset:1088
	s_waitcnt vmcnt(32)
	v_mul_f32_e32 v14, v24, v56
	v_bfe_u32 v15, v14, 16, 1
	v_add3_u32 v18, v14, v15, s33
	v_and_b32_e32 v14, 0xffff0000, v18
	v_fma_f32 v12, v24, v56, -v14
	v_bfe_u32 v15, v12, 16, 1
	v_add3_u32 v12, v12, v15, s33
	v_and_b32_e32 v15, 0xffff0000, v12
	v_add_f32_e32 v14, v14, v15
	v_mul_f32_e32 v15, v24, v88
	v_pk_add_f32 v[8:9], v[8:9], v[14:15]
	v_mul_f32_e32 v14, v40, v57
	v_bfe_u32 v15, v14, 16, 1
	v_add3_u32 v14, v14, v15, s33
	v_and_b32_e32 v15, 0xffff0000, v14
	v_fma_f32 v13, v40, v57, -v15
	v_bfe_u32 v16, v13, 16, 1
	v_add3_u32 v13, v13, v16, s33
	v_perm_b32 v14, v14, v18, s64
	v_perm_b32 v12, v13, v12, s64
	ds_write2st64_b32 v1, v14, v12 offset1:129
	v_and_b32_e32 v12, 0xffff0000, v13
	v_add_f32_e32 v12, v15, v12
	v_mul_f32_e32 v13, v40, v89
	v_pk_add_f32 v[8:9], v[8:9], v[12:13]
	v_add_u32_e32 v1, 4, v1
	global_load_dword v33, v[20:21], off offset:1152
	global_load_dwordx2 v[74:75], v[4:5], off offset:72
	global_load_dwordx2 v[106:107], v[6:7], off offset:72
	global_load_dword v49, v[20:21], off offset:1216
	s_waitcnt vmcnt(32)
	v_mul_f32_e32 v14, v25, v58
	v_bfe_u32 v15, v14, 16, 1
	v_add3_u32 v18, v14, v15, s33
	v_and_b32_e32 v14, 0xffff0000, v18
	v_fma_f32 v12, v25, v58, -v14
	v_bfe_u32 v15, v12, 16, 1
	v_add3_u32 v12, v12, v15, s33
	v_and_b32_e32 v15, 0xffff0000, v12
	v_add_f32_e32 v14, v14, v15
	v_mul_f32_e32 v15, v25, v90
	v_pk_add_f32 v[8:9], v[8:9], v[14:15]
	v_mul_f32_e32 v14, v41, v59
	v_bfe_u32 v15, v14, 16, 1
	v_add3_u32 v14, v14, v15, s33
	v_and_b32_e32 v15, 0xffff0000, v14
	v_fma_f32 v13, v41, v59, -v15
	v_bfe_u32 v16, v13, 16, 1
	v_add3_u32 v13, v13, v16, s33
	v_perm_b32 v14, v14, v18, s64
	v_perm_b32 v12, v13, v12, s64
	ds_write2st64_b32 v1, v14, v12 offset1:129
	v_and_b32_e32 v12, 0xffff0000, v13
	v_add_f32_e32 v12, v15, v12
	v_mul_f32_e32 v13, v41, v91
	v_pk_add_f32 v[8:9], v[8:9], v[12:13]
	v_add_u32_e32 v1, 4, v1
	global_load_dword v34, v[20:21], off offset:1280
	global_load_dwordx2 v[76:77], v[4:5], off offset:80
	global_load_dwordx2 v[108:109], v[6:7], off offset:80
	global_load_dword v50, v[20:21], off offset:1344
	s_waitcnt vmcnt(32)
	v_mul_f32_e32 v14, v26, v60
	v_bfe_u32 v15, v14, 16, 1
	v_add3_u32 v18, v14, v15, s33
	v_and_b32_e32 v14, 0xffff0000, v18
	v_fma_f32 v12, v26, v60, -v14
	v_bfe_u32 v15, v12, 16, 1
	v_add3_u32 v12, v12, v15, s33
	v_and_b32_e32 v15, 0xffff0000, v12
	v_add_f32_e32 v14, v14, v15
	v_mul_f32_e32 v15, v26, v92
	v_pk_add_f32 v[8:9], v[8:9], v[14:15]
	v_mul_f32_e32 v14, v42, v61
	v_bfe_u32 v15, v14, 16, 1
	v_add3_u32 v14, v14, v15, s33
	v_and_b32_e32 v15, 0xffff0000, v14
	v_fma_f32 v13, v42, v61, -v15
	v_bfe_u32 v16, v13, 16, 1
	v_add3_u32 v13, v13, v16, s33
	v_perm_b32 v14, v14, v18, s64
	v_perm_b32 v12, v13, v12, s64
	ds_write2st64_b32 v1, v14, v12 offset1:129
	v_and_b32_e32 v12, 0xffff0000, v13
	v_add_f32_e32 v12, v15, v12
	v_mul_f32_e32 v13, v42, v93
	v_pk_add_f32 v[8:9], v[8:9], v[12:13]
	v_add_u32_e32 v1, 4, v1
	global_load_dword v35, v[20:21], off offset:1408
	global_load_dwordx2 v[78:79], v[4:5], off offset:88
	global_load_dwordx2 v[110:111], v[6:7], off offset:88
	global_load_dword v51, v[20:21], off offset:1472
	s_waitcnt vmcnt(32)
	v_mul_f32_e32 v14, v27, v62
	v_bfe_u32 v15, v14, 16, 1
	v_add3_u32 v18, v14, v15, s33
	v_and_b32_e32 v14, 0xffff0000, v18
	v_fma_f32 v12, v27, v62, -v14
	v_bfe_u32 v15, v12, 16, 1
	v_add3_u32 v12, v12, v15, s33
	v_and_b32_e32 v15, 0xffff0000, v12
	v_add_f32_e32 v14, v14, v15
	v_mul_f32_e32 v15, v27, v94
	v_pk_add_f32 v[8:9], v[8:9], v[14:15]
	v_mul_f32_e32 v14, v43, v63
	v_bfe_u32 v15, v14, 16, 1
	v_add3_u32 v14, v14, v15, s33
	v_and_b32_e32 v15, 0xffff0000, v14
	v_fma_f32 v13, v43, v63, -v15
	v_bfe_u32 v16, v13, 16, 1
	v_add3_u32 v13, v13, v16, s33
	v_perm_b32 v14, v14, v18, s64
	v_perm_b32 v12, v13, v12, s64
	ds_write2st64_b32 v1, v14, v12 offset1:129
	v_and_b32_e32 v12, 0xffff0000, v13
	v_add_f32_e32 v12, v15, v12
	v_mul_f32_e32 v13, v43, v95
	v_pk_add_f32 v[8:9], v[8:9], v[12:13]
	v_add_u32_e32 v1, 4, v1
	global_load_dword v36, v[20:21], off offset:1536
	global_load_dwordx2 v[80:81], v[4:5], off offset:96
	global_load_dwordx2 v[112:113], v[6:7], off offset:96
	global_load_dword v52, v[20:21], off offset:1600
	s_waitcnt vmcnt(32)
	v_mul_f32_e32 v14, v28, v64
	v_bfe_u32 v15, v14, 16, 1
	v_add3_u32 v18, v14, v15, s33
	v_and_b32_e32 v14, 0xffff0000, v18
	v_fma_f32 v12, v28, v64, -v14
	v_bfe_u32 v15, v12, 16, 1
	v_add3_u32 v12, v12, v15, s33
	v_and_b32_e32 v15, 0xffff0000, v12
	v_add_f32_e32 v14, v14, v15
	v_mul_f32_e32 v15, v28, v96
	v_pk_add_f32 v[8:9], v[8:9], v[14:15]
	v_mul_f32_e32 v14, v44, v65
	v_bfe_u32 v15, v14, 16, 1
	v_add3_u32 v14, v14, v15, s33
	v_and_b32_e32 v15, 0xffff0000, v14
	v_fma_f32 v13, v44, v65, -v15
	v_bfe_u32 v16, v13, 16, 1
	v_add3_u32 v13, v13, v16, s33
	v_perm_b32 v14, v14, v18, s64
	v_perm_b32 v12, v13, v12, s64
	ds_write2st64_b32 v1, v14, v12 offset1:129
	v_and_b32_e32 v12, 0xffff0000, v13
	v_add_f32_e32 v12, v15, v12
	v_mul_f32_e32 v13, v44, v97
	v_pk_add_f32 v[8:9], v[8:9], v[12:13]
	v_add_u32_e32 v1, 4, v1
	global_load_dword v37, v[20:21], off offset:1664
	global_load_dwordx2 v[82:83], v[4:5], off offset:104
	global_load_dwordx2 v[114:115], v[6:7], off offset:104
	global_load_dword v53, v[20:21], off offset:1728
	s_waitcnt vmcnt(32)
	v_mul_f32_e32 v14, v29, v66
	v_bfe_u32 v15, v14, 16, 1
	v_add3_u32 v18, v14, v15, s33
	v_and_b32_e32 v14, 0xffff0000, v18
	v_fma_f32 v12, v29, v66, -v14
	v_bfe_u32 v15, v12, 16, 1
	v_add3_u32 v12, v12, v15, s33
	v_and_b32_e32 v15, 0xffff0000, v12
	v_add_f32_e32 v14, v14, v15
	v_mul_f32_e32 v15, v29, v98
	v_pk_add_f32 v[8:9], v[8:9], v[14:15]
	v_mul_f32_e32 v14, v45, v67
	v_bfe_u32 v15, v14, 16, 1
	v_add3_u32 v14, v14, v15, s33
	v_and_b32_e32 v15, 0xffff0000, v14
	v_fma_f32 v13, v45, v67, -v15
	v_bfe_u32 v16, v13, 16, 1
	v_add3_u32 v13, v13, v16, s33
	v_perm_b32 v14, v14, v18, s64
	v_perm_b32 v12, v13, v12, s64
	ds_write2st64_b32 v1, v14, v12 offset1:129
	v_and_b32_e32 v12, 0xffff0000, v13
	v_add_f32_e32 v12, v15, v12
	v_mul_f32_e32 v13, v45, v99
	v_pk_add_f32 v[8:9], v[8:9], v[12:13]
	v_add_u32_e32 v1, 4, v1
	global_load_dword v38, v[20:21], off offset:1792
	global_load_dwordx2 v[84:85], v[4:5], off offset:112
	global_load_dwordx2 v[116:117], v[6:7], off offset:112
	global_load_dword v54, v[20:21], off offset:1856
	s_waitcnt vmcnt(32)
	v_mul_f32_e32 v14, v30, v68
	v_bfe_u32 v15, v14, 16, 1
	v_add3_u32 v18, v14, v15, s33
	v_and_b32_e32 v14, 0xffff0000, v18
	v_fma_f32 v12, v30, v68, -v14
	v_bfe_u32 v15, v12, 16, 1
	v_add3_u32 v12, v12, v15, s33
	v_and_b32_e32 v15, 0xffff0000, v12
	v_add_f32_e32 v14, v14, v15
	v_mul_f32_e32 v15, v30, v100
	v_pk_add_f32 v[8:9], v[8:9], v[14:15]
	v_mul_f32_e32 v14, v46, v69
	v_bfe_u32 v15, v14, 16, 1
	v_add3_u32 v14, v14, v15, s33
	v_and_b32_e32 v15, 0xffff0000, v14
	v_fma_f32 v13, v46, v69, -v15
	v_bfe_u32 v16, v13, 16, 1
	v_add3_u32 v13, v13, v16, s33
	v_perm_b32 v14, v14, v18, s64
	v_perm_b32 v12, v13, v12, s64
	ds_write2st64_b32 v1, v14, v12 offset1:129
	v_and_b32_e32 v12, 0xffff0000, v13
	v_add_f32_e32 v12, v15, v12
	v_mul_f32_e32 v13, v46, v101
	v_pk_add_f32 v[8:9], v[8:9], v[12:13]
	v_add_u32_e32 v1, 4, v1
	global_load_dword v39, v[20:21], off offset:1920
	global_load_dwordx2 v[86:87], v[4:5], off offset:120
	global_load_dwordx2 v[118:119], v[6:7], off offset:120
	global_load_dword v55, v[20:21], off offset:1984
	s_waitcnt vmcnt(32)
	v_mul_f32_e32 v14, v31, v70
	v_bfe_u32 v15, v14, 16, 1
	v_add3_u32 v18, v14, v15, s33
	v_and_b32_e32 v14, 0xffff0000, v18
	v_fma_f32 v12, v31, v70, -v14
	v_bfe_u32 v15, v12, 16, 1
	v_add3_u32 v12, v12, v15, s33
	v_and_b32_e32 v15, 0xffff0000, v12
	v_add_f32_e32 v14, v14, v15
	v_mul_f32_e32 v15, v31, v102
	v_pk_add_f32 v[8:9], v[8:9], v[14:15]
	v_mul_f32_e32 v14, v47, v71
	v_bfe_u32 v15, v14, 16, 1
	v_add3_u32 v14, v14, v15, s33
	v_and_b32_e32 v15, 0xffff0000, v14
	v_fma_f32 v13, v47, v71, -v15
	v_bfe_u32 v16, v13, 16, 1
	v_add3_u32 v13, v13, v16, s33
	v_perm_b32 v14, v14, v18, s64
	v_perm_b32 v12, v13, v12, s64
	ds_write2st64_b32 v1, v14, v12 offset1:129
	v_and_b32_e32 v12, 0xffff0000, v13
	v_add_f32_e32 v12, v15, v12
	v_mul_f32_e32 v13, v47, v103
	v_pk_add_f32 v[8:9], v[8:9], v[12:13]
	v_add_u32_e32 v1, 4, v1
	s_waitcnt vmcnt(28)
	v_mul_f32_e32 v14, v32, v72
	v_bfe_u32 v15, v14, 16, 1
	v_add3_u32 v18, v14, v15, s33
	v_and_b32_e32 v14, 0xffff0000, v18
	v_fma_f32 v12, v32, v72, -v14
	v_bfe_u32 v15, v12, 16, 1
	v_add3_u32 v12, v12, v15, s33
	v_and_b32_e32 v15, 0xffff0000, v12
	v_add_f32_e32 v14, v14, v15
	v_mul_f32_e32 v15, v32, v104
	v_pk_add_f32 v[8:9], v[8:9], v[14:15]
	v_mul_f32_e32 v14, v48, v73
	v_bfe_u32 v15, v14, 16, 1
	v_add3_u32 v14, v14, v15, s33
	v_and_b32_e32 v15, 0xffff0000, v14
	v_fma_f32 v13, v48, v73, -v15
	v_bfe_u32 v16, v13, 16, 1
	v_add3_u32 v13, v13, v16, s33
	v_perm_b32 v14, v14, v18, s64
	v_perm_b32 v12, v13, v12, s64
	ds_write2st64_b32 v1, v14, v12 offset1:129
	v_and_b32_e32 v12, 0xffff0000, v13
	v_add_f32_e32 v12, v15, v12
	v_mul_f32_e32 v13, v48, v105
	v_pk_add_f32 v[8:9], v[8:9], v[12:13]
	v_add_u32_e32 v1, 4, v1
	s_waitcnt vmcnt(24)
	v_mul_f32_e32 v14, v33, v74
	v_bfe_u32 v15, v14, 16, 1
	v_add3_u32 v18, v14, v15, s33
	v_and_b32_e32 v14, 0xffff0000, v18
	v_fma_f32 v12, v33, v74, -v14
	v_bfe_u32 v15, v12, 16, 1
	v_add3_u32 v12, v12, v15, s33
	v_and_b32_e32 v15, 0xffff0000, v12
	v_add_f32_e32 v14, v14, v15
	v_mul_f32_e32 v15, v33, v106
	v_pk_add_f32 v[8:9], v[8:9], v[14:15]
	v_mul_f32_e32 v14, v49, v75
	v_bfe_u32 v15, v14, 16, 1
	v_add3_u32 v14, v14, v15, s33
	v_and_b32_e32 v15, 0xffff0000, v14
	v_fma_f32 v13, v49, v75, -v15
	v_bfe_u32 v16, v13, 16, 1
	v_add3_u32 v13, v13, v16, s33
	v_perm_b32 v14, v14, v18, s64
	v_perm_b32 v12, v13, v12, s64
	ds_write2st64_b32 v1, v14, v12 offset1:129
	v_and_b32_e32 v12, 0xffff0000, v13
	v_add_f32_e32 v12, v15, v12
	v_mul_f32_e32 v13, v49, v107
	v_pk_add_f32 v[8:9], v[8:9], v[12:13]
	v_add_u32_e32 v1, 4, v1
	s_waitcnt vmcnt(20)
	v_mul_f32_e32 v14, v34, v76
	v_bfe_u32 v15, v14, 16, 1
	v_add3_u32 v18, v14, v15, s33
	v_and_b32_e32 v14, 0xffff0000, v18
	v_fma_f32 v12, v34, v76, -v14
	v_bfe_u32 v15, v12, 16, 1
	v_add3_u32 v12, v12, v15, s33
	v_and_b32_e32 v15, 0xffff0000, v12
	v_add_f32_e32 v14, v14, v15
	v_mul_f32_e32 v15, v34, v108
	v_pk_add_f32 v[8:9], v[8:9], v[14:15]
	v_mul_f32_e32 v14, v50, v77
	v_bfe_u32 v15, v14, 16, 1
	v_add3_u32 v14, v14, v15, s33
	v_and_b32_e32 v15, 0xffff0000, v14
	v_fma_f32 v13, v50, v77, -v15
	v_bfe_u32 v16, v13, 16, 1
	v_add3_u32 v13, v13, v16, s33
	v_perm_b32 v14, v14, v18, s64
	v_perm_b32 v12, v13, v12, s64
	ds_write2st64_b32 v1, v14, v12 offset1:129
	v_and_b32_e32 v12, 0xffff0000, v13
	v_add_f32_e32 v12, v15, v12
	v_mul_f32_e32 v13, v50, v109
	v_pk_add_f32 v[8:9], v[8:9], v[12:13]
	v_add_u32_e32 v1, 4, v1
	s_waitcnt vmcnt(16)
	v_mul_f32_e32 v14, v35, v78
	v_bfe_u32 v15, v14, 16, 1
	v_add3_u32 v18, v14, v15, s33
	v_and_b32_e32 v14, 0xffff0000, v18
	v_fma_f32 v12, v35, v78, -v14
	v_bfe_u32 v15, v12, 16, 1
	v_add3_u32 v12, v12, v15, s33
	v_and_b32_e32 v15, 0xffff0000, v12
	v_add_f32_e32 v14, v14, v15
	v_mul_f32_e32 v15, v35, v110
	v_pk_add_f32 v[8:9], v[8:9], v[14:15]
	v_mul_f32_e32 v14, v51, v79
	v_bfe_u32 v15, v14, 16, 1
	v_add3_u32 v14, v14, v15, s33
	v_and_b32_e32 v15, 0xffff0000, v14
	v_fma_f32 v13, v51, v79, -v15
	v_bfe_u32 v16, v13, 16, 1
	v_add3_u32 v13, v13, v16, s33
	v_perm_b32 v14, v14, v18, s64
	v_perm_b32 v12, v13, v12, s64
	ds_write2st64_b32 v1, v14, v12 offset1:129
	v_and_b32_e32 v12, 0xffff0000, v13
	v_add_f32_e32 v12, v15, v12
	v_mul_f32_e32 v13, v51, v111
	v_pk_add_f32 v[8:9], v[8:9], v[12:13]
	v_add_u32_e32 v1, 4, v1
	s_waitcnt vmcnt(12)
	v_mul_f32_e32 v14, v36, v80
	v_bfe_u32 v15, v14, 16, 1
	v_add3_u32 v18, v14, v15, s33
	v_and_b32_e32 v14, 0xffff0000, v18
	v_fma_f32 v12, v36, v80, -v14
	v_bfe_u32 v15, v12, 16, 1
	v_add3_u32 v12, v12, v15, s33
	v_and_b32_e32 v15, 0xffff0000, v12
	v_add_f32_e32 v14, v14, v15
	v_mul_f32_e32 v15, v36, v112
	v_pk_add_f32 v[8:9], v[8:9], v[14:15]
	v_mul_f32_e32 v14, v52, v81
	v_bfe_u32 v15, v14, 16, 1
	v_add3_u32 v14, v14, v15, s33
	v_and_b32_e32 v15, 0xffff0000, v14
	v_fma_f32 v13, v52, v81, -v15
	v_bfe_u32 v16, v13, 16, 1
	v_add3_u32 v13, v13, v16, s33
	v_perm_b32 v14, v14, v18, s64
	v_perm_b32 v12, v13, v12, s64
	ds_write2st64_b32 v1, v14, v12 offset1:129
	v_and_b32_e32 v12, 0xffff0000, v13
	v_add_f32_e32 v12, v15, v12
	v_mul_f32_e32 v13, v52, v113
	v_pk_add_f32 v[8:9], v[8:9], v[12:13]
	v_add_u32_e32 v1, 4, v1
	s_waitcnt vmcnt(8)
	v_mul_f32_e32 v14, v37, v82
	v_bfe_u32 v15, v14, 16, 1
	v_add3_u32 v18, v14, v15, s33
	v_and_b32_e32 v14, 0xffff0000, v18
	v_fma_f32 v12, v37, v82, -v14
	v_bfe_u32 v15, v12, 16, 1
	v_add3_u32 v12, v12, v15, s33
	v_and_b32_e32 v15, 0xffff0000, v12
	v_add_f32_e32 v14, v14, v15
	v_mul_f32_e32 v15, v37, v114
	v_pk_add_f32 v[8:9], v[8:9], v[14:15]
	v_mul_f32_e32 v14, v53, v83
	v_bfe_u32 v15, v14, 16, 1
	v_add3_u32 v14, v14, v15, s33
	v_and_b32_e32 v15, 0xffff0000, v14
	v_fma_f32 v13, v53, v83, -v15
	v_bfe_u32 v16, v13, 16, 1
	v_add3_u32 v13, v13, v16, s33
	v_perm_b32 v14, v14, v18, s64
	v_perm_b32 v12, v13, v12, s64
	ds_write2st64_b32 v1, v14, v12 offset1:129
	v_and_b32_e32 v12, 0xffff0000, v13
	v_add_f32_e32 v12, v15, v12
	v_mul_f32_e32 v13, v53, v115
	v_pk_add_f32 v[8:9], v[8:9], v[12:13]
	v_add_u32_e32 v1, 4, v1
	s_waitcnt vmcnt(4)
	v_mul_f32_e32 v14, v38, v84
	v_bfe_u32 v15, v14, 16, 1
	v_add3_u32 v18, v14, v15, s33
	v_and_b32_e32 v14, 0xffff0000, v18
	v_fma_f32 v12, v38, v84, -v14
	v_bfe_u32 v15, v12, 16, 1
	v_add3_u32 v12, v12, v15, s33
	v_and_b32_e32 v15, 0xffff0000, v12
	v_add_f32_e32 v14, v14, v15
	v_mul_f32_e32 v15, v38, v116
	v_pk_add_f32 v[8:9], v[8:9], v[14:15]
	v_mul_f32_e32 v14, v54, v85
	v_bfe_u32 v15, v14, 16, 1
	v_add3_u32 v14, v14, v15, s33
	v_and_b32_e32 v15, 0xffff0000, v14
	v_fma_f32 v13, v54, v85, -v15
	v_bfe_u32 v16, v13, 16, 1
	v_add3_u32 v13, v13, v16, s33
	v_perm_b32 v14, v14, v18, s64
	v_perm_b32 v12, v13, v12, s64
	ds_write2st64_b32 v1, v14, v12 offset1:129
	v_and_b32_e32 v12, 0xffff0000, v13
	v_add_f32_e32 v12, v15, v12
	v_mul_f32_e32 v13, v54, v117
	v_pk_add_f32 v[8:9], v[8:9], v[12:13]
	v_add_u32_e32 v1, 4, v1
	s_waitcnt vmcnt(0)
	v_mul_f32_e32 v14, v39, v86
	v_bfe_u32 v15, v14, 16, 1
	v_add3_u32 v18, v14, v15, s33
	v_and_b32_e32 v14, 0xffff0000, v18
	v_fma_f32 v12, v39, v86, -v14
	v_bfe_u32 v15, v12, 16, 1
	v_add3_u32 v12, v12, v15, s33
	v_and_b32_e32 v15, 0xffff0000, v12
	v_add_f32_e32 v14, v14, v15
	v_mul_f32_e32 v15, v39, v118
	v_pk_add_f32 v[8:9], v[8:9], v[14:15]
	v_mul_f32_e32 v14, v55, v87
	v_bfe_u32 v15, v14, 16, 1
	v_add3_u32 v14, v14, v15, s33
	v_and_b32_e32 v15, 0xffff0000, v14
	v_fma_f32 v13, v55, v87, -v15
	v_bfe_u32 v16, v13, 16, 1
	v_add3_u32 v13, v13, v16, s33
	v_perm_b32 v14, v14, v18, s64
	v_perm_b32 v12, v13, v12, s64
	ds_write2st64_b32 v1, v14, v12 offset1:129
	v_and_b32_e32 v12, 0xffff0000, v13
	v_add_f32_e32 v12, v15, v12
	v_mul_f32_e32 v13, v55, v119
	v_pk_add_f32 v[8:9], v[8:9], v[12:13]
	v_add_u32_e32 v1, 4, v1
	s_lshl_b32 s16, s65, 10
	s_mov_b32 s17, s75
	v_writelane_b32 v255, s16, 28
	v_and_b32_e32 v1, 0x3ffffff0, v0
	v_lshlrev_b32_e32 v1, 2, v1
	v_writelane_b32 v255, s17, 29
	v_readlane_b32 s16, v254, 46
	v_lshlrev_b32_e32 v6, 2, v10
	s_nop 0
	v_lshl_add_u32 v2, v0, 2, s16
	v_add3_u32 v1, s16, v1, v6
	s_movk_i32 s16, 0x400
	v_cmp_gt_i32_e32 vcc, s16, v0
	ds_write_b32 v2, v8
	ds_write_b32 v1, v9 offset:2048
	s_and_saveexec_b64 s[16:17], vcc
	s_mov_b32 s70, 0xffff
	s_cbranch_execz .LBB0_428
	v_max_i32_e32 v1, 0x200, v0
	v_sub_u32_e32 v1, v1, v0
	v_add_u32_e32 v1, 0x1ff, v1
	s_movk_i32 s25, 0x2600
	v_cmp_gt_u32_e64 s[36:37], s25, v1
	s_movk_i32 s25, 0x25ff
	v_cmp_lt_u32_e32 vcc, s25, v1
	v_mov_b32_e32 v2, v0
	s_and_saveexec_b64 s[44:45], vcc
	s_cbranch_execz .LBB0_425
	v_lshlrev_b32_e32 v5, 2, v0
	v_readlane_b32 s25, v254, 47
	v_lshlrev_b32_e32 v3, 2, v1
	v_and_b32_e32 v3, 0xfffff800, v3
	v_add_u32_e32 v2, s25, v5
	v_add_u32_e32 v3, v2, v3
	v_cmp_gt_u32_e32 vcc, 2.0, v1
	v_cmp_ge_u32_e64 s[38:39], v3, v2
	s_and_b64 s[50:51], s[38:39], vcc
	s_mov_b64 s[48:49], -1
	v_mov_b32_e32 v2, v0
	s_and_saveexec_b64 s[38:39], s[50:51]
	s_cbranch_execz .LBB0_424
	v_readlane_b32 s48, v255, 28
	v_readlane_b32 s49, v255, 29
	s_lshl_b64 s[50:51], s[48:49], 2
	v_lshrrev_b32_e32 v4, 9, v1
	s_add_u32 s48, s40, s50
	s_addc_u32 s49, s41, s51
	v_add_u32_e32 v2, -1, v4
	s_add_u32 s50, s42, s50
	v_add_u32_e32 v1, 0x200, v0
	v_lshrrev_b32_e32 v3, 1, v2
	s_addc_u32 s51, s43, s51
	v_add_u32_e32 v7, 1, v3
	v_cmp_lt_u32_e32 vcc, 5, v2
	v_mov_b32_e32 v12, 0
	v_mov_b64_e32 v[2:3], v[0:1]
	s_and_saveexec_b64 s[52:53], vcc
	s_cbranch_execz .LBB0_420
	v_readlane_b32 s25, v254, 48
	v_and_b32_e32 v8, -4, v7
	s_mov_b64 s[54:55], 0
	v_add_u32_e32 v9, s25, v5
	s_mov_b32 s25, 0
	v_mov_b64_e32 v[2:3], v[0:1]
